# v13_combo_dbuf
# speedup vs baseline: 1.0184x; 1.0034x over previous
; #define MFMA32(a, b, c) __builtin_amdgcn_mfma_f32_32x32x16_bf16((a), (b), (c), 0, 0, 0)
; DI f32x16 zero16() { f32x16 z; for (int i = 0; i < 16; ++i) z[i] = 0.f; return z; }
; template <int DQK, int MODE>
; DI void attn_core(const u16* __restrict__ Qg, int ldq, const u16* __restrict__ Kg, int ldk, const u16* __restrict__ Vtg,
;                   const u64* __restrict__ maskg, int q0, float scale, char* smem, int* sflags, f32x16 (&o)[4], float& l_run) {
;     ...
;   for (int it = 0; it < ntiles; ++it, tau += step) {
;     __syncthreads();
;     if (MODE == 2 && it > 0) {
;       if (!(sflags[0] | sflags[1] | sflags[2] | sflags[3] | sflags[4] | sflags[5] | sflags[6] | sflags[7])) break;
;     }
;     if (MODE == 2) gload(tau);
; #pragma unroll
;     for (int i = 0; i < NVK; ++i) {
;       const int v = tid + NT * i, row = v / VPR, c = v % VPR;
;       *(u32x4*)(Ks + row * KSTR + c * 8) = rk[i];
;     }
; #pragma unroll
;     for (int i = 0; i < 2; ++i) {
;       const int v = tid + NT * i, row = v >> 3, c = v & 7;
;       *(u32x4*)(Vs + row * 72 + c * 8) = rv[i];
;     }
;     __syncthreads();
;     if (MODE != 2 && it + 1 < ntiles) gload(tau + step);
;     if (tau * 64 > q0 + 32 * wid + 31) {
;       if (MODE == 2 && lane == 0) sflags[wid] = 1;
;       continue;
;     }
;     u64 mbits = 0;
;     if (MODE == 1) mbits = maskg[(long)qrow * 64 + tau] >> (8 * hh);
;     f32x16 s[2];
;     s[0] = zero16(); s[1] = zero16();
; #pragma unroll
;     for (int kt = 0; kt < 2; ++kt)
; #pragma unroll
;       for (int ks = 0; ks < NKS; ++ks) {
;         const bf16x8 kf = *(const bf16x8*)(Ks + (32 * kt + krow) * KSTR + ks * 16 + hh * 8);
;         s[kt] = MFMA32(kf, qf[ks], s[kt]);
;       }
;     const int kbase = tau * 64 + 8 * hh;
;     if (MODE == 0 || MODE == 1) {
;       const bool need_mask = (MODE == 1) || (tau * 64 + 63 > q0 + 32 * wid);
;       float mx = -1e30f;
;       if (need_mask) {
; #pragma unroll
;         for (int kt = 0; kt < 2; ++kt)
; #pragma unroll
;           for (int i = 0; i < 16; ++i) {
;             bool valid;
;             if (MODE == 1) valid = (mbits >> (32 * kt + 16 * (i >> 3) + (i & 7))) & 1ull;
;             else valid = (kbase + 32 * kt + 16 * (i >> 3) + (i & 7)) <= qrow;
;             s[kt][i] = valid ? s[kt][i] : -1e30f;
;           }
.LBB0_155:
	s_or_b64 exec, exec, s[4:5]
	v_xor_b32_e32 v180, 0x10000, v180
	v_xor_b32_e32 v181, 0x10000, v181
	v_xor_b32_e32 v182, 0x10000, v182
	v_xor_b32_e32 v183, 0x10000, v183
	v_xor_b32_e32 v174, 0x10000, v174
	s_add_i32 s15, s15, 1
	s_add_i32 s0, s0, 64
	s_cmp_eq_u32 s14, s15
	v_lshl_add_u64 v[172:173], v[172:173], 0, 8
	s_cbranch_scc1 .LBB0_159
.LBB0_156:
	v_add_u32_e32 v0, s0, v176
	v_mad_i64_i32 v[2:3], s[4:5], v0, s75, v[168:169]
	v_add_u32_e32 v0, s0, v177
	v_mad_i64_i32 v[4:5], s[4:5], v0, s75, v[170:171]
	s_ashr_i32 s1, s0, 31
	s_lshl_b64 s[4:5], s[0:1], 1
	s_nop 0
	s_waitcnt vmcnt(0)
	ds_write_b128 v180, v[156:159]
	ds_write_b128 v181, v[152:155]
	ds_write_b128 v182, v[148:151] offset:17408
	ds_write_b128 v183, v[144:147] offset:17408
	s_waitcnt lgkmcnt(0)
	s_barrier
	global_load_dwordx4 v[156:159], v[2:3], off
	global_load_dwordx4 v[152:155], v[4:5], off
	v_lshl_add_u64 v[2:3], v[162:163], 0, s[4:5]
	v_lshl_add_u64 v[4:5], v[166:167], 0, s[4:5]
	global_load_dwordx4 v[148:151], v[2:3], off
	global_load_dwordx4 v[144:147], v[4:5], off
	s_sub_i32 s1, s0, 64
	v_cmp_le_i32_e32 vcc, s1, v179
	s_and_saveexec_b64 s[4:5], vcc
	s_cbranch_execz .LBB0_155
	v_add_u32_e32 v0, v174, v178
	global_load_dwordx2 v[10:11], v[172:173], off
	ds_read_b128 v[12:15], v0
	ds_read_b128 v[202:205], v0 offset:32
	ds_read_b128 v[210:213], v0 offset:64
	ds_read_b128 v[214:217], v0 offset:96
	ds_read_b128 v[218:221], v0 offset:128
	ds_read_b128 v[226:229], v0 offset:160
	s_waitcnt lgkmcnt(5)
	v_mfma_f32_32x32x16_bf16 v[96:111], v[12:15], v[140:143], 0
	ds_read_b128 v[12:15], v0 offset:192
	s_waitcnt lgkmcnt(5)
	v_mfma_f32_32x32x16_bf16 v[96:111], v[202:205], v[136:139], v[96:111]
	ds_read_b128 v[202:205], v0 offset:224
	s_waitcnt vmcnt(0)
	v_lshrrev_b64 v[8:9], v160, v[10:11]
	s_waitcnt lgkmcnt(5)
	v_mfma_f32_32x32x16_bf16 v[96:111], v[210:213], v[132:135], v[96:111]
	ds_read_b128 v[210:213], v0 offset:8704
	s_waitcnt lgkmcnt(5)
	v_mfma_f32_32x32x16_bf16 v[96:111], v[214:217], v[128:131], v[96:111]
	ds_read_b128 v[214:217], v0 offset:8736
	s_waitcnt lgkmcnt(5)
	v_mfma_f32_32x32x16_bf16 v[96:111], v[218:221], v[124:127], v[96:111]
	ds_read_b128 v[218:221], v0 offset:8768
	s_waitcnt lgkmcnt(5)
	v_mfma_f32_32x32x16_bf16 v[96:111], v[226:229], v[120:123], v[96:111]
	ds_read_b128 v[226:229], v0 offset:8800
	s_waitcnt lgkmcnt(5)
	v_mfma_f32_32x32x16_bf16 v[96:111], v[12:15], v[116:119], v[96:111]
	ds_read_b128 v[12:15], v0 offset:8832
	s_waitcnt lgkmcnt(5)
	v_mfma_f32_32x32x16_bf16 v[96:111], v[202:205], v[112:115], v[96:111]
	ds_read_b128 v[202:205], v0 offset:8864
	s_waitcnt lgkmcnt(5)
	v_mfma_f32_32x32x16_bf16 v[80:95], v[210:213], v[140:143], 0
	ds_read_b128 v[210:213], v0 offset:8896
	s_waitcnt lgkmcnt(5)
	v_mfma_f32_32x32x16_bf16 v[80:95], v[214:217], v[136:139], v[80:95]
	ds_read_b128 v[214:217], v0 offset:8928
	s_waitcnt lgkmcnt(5)
	v_mfma_f32_32x32x16_bf16 v[80:95], v[218:221], v[132:135], v[80:95]
	s_waitcnt lgkmcnt(4)
	v_mfma_f32_32x32x16_bf16 v[80:95], v[226:229], v[128:131], v[80:95]
	s_waitcnt lgkmcnt(3)
	v_mfma_f32_32x32x16_bf16 v[80:95], v[12:15], v[124:127], v[80:95]
	s_waitcnt lgkmcnt(2)
	v_mfma_f32_32x32x16_bf16 v[80:95], v[202:205], v[120:123], v[80:95]
	s_waitcnt lgkmcnt(1)
	v_mfma_f32_32x32x16_bf16 v[80:95], v[210:213], v[116:119], v[80:95]
	v_lshrrev_b32_e32 v0, v160, v10
	v_and_b32_e32 v0, 1, v0
	v_cmp_eq_u32_e32 vcc, 1, v0
	v_and_b32_e32 v0, 2, v8
	s_nop 0
	v_cndmask_b32_e32 v200, v225, v96, vcc
	v_cmp_ne_u32_e32 vcc, 0, v0
	v_and_b32_e32 v0, 4, v8
	s_waitcnt lgkmcnt(0)
	v_mfma_f32_32x32x16_bf16 v[80:95], v[214:217], v[112:115], v[80:95]
	v_cndmask_b32_e32 v187, v225, v97, vcc
	v_cmp_ne_u32_e32 vcc, 0, v0
	v_and_b32_e32 v0, 8, v8
	v_mbcnt_hi_u32_b32 v2, -1, v223
	v_cndmask_b32_e32 v199, v225, v98, vcc
	v_cmp_ne_u32_e32 vcc, 0, v0
	v_and_b32_e32 v0, 16, v8
	s_nop 0
	v_cndmask_b32_e32 v198, v225, v99, vcc
	v_cmp_ne_u32_e32 vcc, 0, v0
	v_and_b32_e32 v0, 32, v8
	s_nop 0
	v_cndmask_b32_e32 v201, v225, v100, vcc
	v_cmp_ne_u32_e32 vcc, 0, v0
	v_and_b32_e32 v0, 64, v8
	s_nop 0
	v_cndmask_b32_e32 v96, v225, v101, vcc
	v_cmp_ne_u32_e32 vcc, 0, v0
	v_and_b32_e32 v0, 0x80, v8
	s_nop 0
	v_cndmask_b32_e32 v186, v225, v102, vcc
	v_cmp_ne_u32_e32 vcc, 0, v0
	v_and_b32_e32 v0, 0x10000, v8
	s_nop 0
	v_cndmask_b32_e32 v97, v225, v103, vcc
	v_cmp_ne_u32_e32 vcc, 0, v0
	v_and_b32_e32 v0, 0x20000, v8
	s_nop 0
	v_cndmask_b32_e32 v185, v225, v104, vcc
	v_cmp_ne_u32_e32 vcc, 0, v0
	v_and_b32_e32 v0, 0x40000, v8
	s_nop 0
	v_cndmask_b32_e32 v105, v225, v105, vcc
	v_cmp_ne_u32_e32 vcc, 0, v0
	v_and_b32_e32 v0, 0x80000, v8
	s_nop 0
	v_cndmask_b32_e32 v104, v225, v106, vcc
	v_cmp_ne_u32_e32 vcc, 0, v0
	v_and_b32_e32 v0, 0x100000, v8
	s_nop 0
	v_cndmask_b32_e32 v103, v225, v107, vcc
	v_cmp_ne_u32_e32 vcc, 0, v0
	v_and_b32_e32 v0, 0x200000, v8
	s_nop 0
	v_cndmask_b32_e32 v102, v225, v108, vcc
	v_cmp_ne_u32_e32 vcc, 0, v0
	v_and_b32_e32 v0, 0x400000, v8
	s_nop 0
	v_cndmask_b32_e32 v10, v225, v109, vcc
	v_cmp_ne_u32_e32 vcc, 0, v0
	v_and_b32_e32 v0, 0x800000, v8
	s_nop 0
	v_cndmask_b32_e32 v100, v225, v110, vcc
	v_cmp_ne_u32_e32 vcc, 0, v0
	v_and_b32_e32 v0, 1, v9
	s_nop 0
	v_cndmask_b32_e32 v11, v225, v111, vcc
	v_cmp_eq_u32_e32 vcc, 1, v0
	v_and_b32_e32 v0, 2, v9
	s_nop 0
	v_cndmask_b32_e32 v101, v225, v80, vcc
	v_cmp_ne_u32_e32 vcc, 0, v0
	v_and_b32_e32 v0, 4, v9
	s_nop 0
	v_cndmask_b32_e32 v99, v225, v81, vcc
	v_cmp_ne_u32_e32 vcc, 0, v0
	v_and_b32_e32 v0, 8, v9
	s_nop 0
	v_cndmask_b32_e32 v12, v225, v82, vcc
	v_cmp_ne_u32_e32 vcc, 0, v0
	v_and_b32_e32 v0, 16, v9
	v_xor_b32_e32 v82, 32, v2
	v_cndmask_b32_e32 v13, v225, v83, vcc
	v_cmp_ne_u32_e32 vcc, 0, v0
; template <int DQK, int MODE>
; DI void attn_core(const u16* __restrict__ Qg, int ldq, const u16* __restrict__ Kg, int ldk, const u16* __restrict__ Vtg,
;                   const u64* __restrict__ maskg, int q0, float scale, char* smem, int* sflags, f32x16 (&o)[4], float& l_run) {
;     ...
;   for (int it = 0; it < ntiles; ++it, tau += step) {
;     __syncthreads();
;     if (MODE == 2 && it > 0) {
;       if (!(sflags[0] | sflags[1] | sflags[2] | sflags[3] | sflags[4] | sflags[5] | sflags[6] | sflags[7])) break;
;     }
;     if (MODE == 2) gload(tau);
; #pragma unroll
;     for (int i = 0; i < NVK; ++i) {
;       const int v = tid + NT * i, row = v / VPR, c = v % VPR;
;       *(u32x4*)(Ks + row * KSTR + c * 8) = rk[i];
;     }
; #pragma unroll
;     for (int i = 0; i < 2; ++i) {
;       const int v = tid + NT * i, row = v >> 3, c = v & 7;
;       *(u32x4*)(Vs + row * 72 + c * 8) = rv[i];
;     }
;     __syncthreads();
;     ...
;       float mx = -1e30f;
;       if (need_mask) {
; #pragma unroll
;         for (int kt = 0; kt < 2; ++kt)
; #pragma unroll
;           for (int i = 0; i < 16; ++i) {
;             bool valid;
;             if (MODE == 1) valid = (mbits >> (32 * kt + 16 * (i >> 3) + (i & 7))) & 1ull;
;             else valid = (kbase + 32 * kt + 16 * (i >> 3) + (i & 7)) <= qrow;
;             s[kt][i] = valid ? s[kt][i] : -1e30f;
;           }
;       }
; #pragma unroll
;       for (int kt = 0; kt < 2; ++kt)
; #pragma unroll
;         for (int i = 0; i < 16; ++i) mx = fmaxf(mx, s[kt][i]);
;       mx = fmaxf(mx, __shfl_xor(mx, 32));
;       const float m_new = fmaxf(m_run, mx);
;       const float alpha = __builtin_amdgcn_exp2f((m_run - m_new) * sc);
;       m_run = m_new;
;       const float msc = -m_new * sc;
;       float ls = 0.f;
; #pragma unroll
;       for (int kt = 0; kt < 2; ++kt)
; #pragma unroll
;         for (int i = 0; i < 16; ++i) {
;           float pv = __builtin_amdgcn_exp2f(__builtin_fmaf(s[kt][i], sc, msc));
;           if (MODE == 1) pv = (s[kt][i] > -1e29f) ? pv : 0.f;
;           s[kt][i] = pv;
;           ls += pv;
;         }
;       if (__any(alpha != 1.0f)) {
;         l_run *= alpha;
; #pragma unroll
;         for (int t = 0; t < 4; ++t)
; #pragma unroll
;           for (int i = 0; i < 16; ++i) o[t][i] *= alpha;
;       }
	v_and_b32_e32 v0, 32, v9
	v_and_b32_e32 v83, 64, v2
	v_cndmask_b32_e32 v14, v225, v84, vcc
	v_cmp_ne_u32_e32 vcc, 0, v0
	v_and_b32_e32 v0, 64, v9
	v_add_u32_e32 v83, 64, v83
	v_cndmask_b32_e32 v15, v225, v85, vcc
	v_cmp_ne_u32_e32 vcc, 0, v0
	v_and_b32_e32 v0, 0x80, v9
	s_nop 0
	v_cndmask_b32_e32 v80, v225, v86, vcc
	v_cmp_ne_u32_e32 vcc, 0, v0
	v_and_b32_e32 v0, 0x10000, v9
	s_nop 0
	v_cndmask_b32_e32 v81, v225, v87, vcc
	v_cmp_ne_u32_e32 vcc, 0, v0
	v_and_b32_e32 v0, 0x20000, v9
	s_nop 0
	v_cndmask_b32_e32 v98, v225, v88, vcc
	v_cmp_ne_u32_e32 vcc, 0, v0
	v_and_b32_e32 v0, 0x40000, v9
	s_nop 0
	v_cndmask_b32_e32 v3, v225, v89, vcc
	v_cmp_ne_u32_e32 vcc, 0, v0
	v_and_b32_e32 v0, 0x80000, v9
	s_nop 0
	v_cndmask_b32_e32 v4, v225, v90, vcc
	v_cmp_ne_u32_e32 vcc, 0, v0
	v_and_b32_e32 v0, 0x100000, v9
	s_nop 0
	v_cndmask_b32_e32 v5, v225, v91, vcc
	v_cmp_ne_u32_e32 vcc, 0, v0
	v_and_b32_e32 v0, 0x200000, v9
	s_nop 0
	v_cndmask_b32_e32 v6, v225, v92, vcc
	v_cmp_ne_u32_e32 vcc, 0, v0
	v_and_b32_e32 v0, 0x400000, v9
	s_nop 0
	v_cndmask_b32_e32 v7, v225, v93, vcc
	v_cmp_ne_u32_e32 vcc, 0, v0
	v_and_b32_e32 v0, 0x800000, v9
	s_nop 0
	v_cndmask_b32_e32 v8, v225, v94, vcc
	v_cmp_ne_u32_e32 vcc, 0, v0
	v_max3_f32 v0, v200, s58, v187
	v_max3_f32 v0, v0, v199, v198
	v_max3_f32 v0, v0, v201, v96
	v_max3_f32 v0, v0, v186, v97
	v_max3_f32 v0, v0, v185, v105
	v_max3_f32 v0, v0, v104, v103
	v_max3_f32 v0, v0, v102, v10
	v_max3_f32 v0, v0, v100, v11
	v_max3_f32 v0, v0, v101, v99
	v_max3_f32 v0, v0, v12, v13
	v_max3_f32 v0, v0, v14, v15
	v_max3_f32 v0, v0, v80, v81
	v_max3_f32 v0, v0, v98, v3
	v_cndmask_b32_e32 v9, v225, v95, vcc
	v_max3_f32 v0, v0, v4, v5
	v_cmp_lt_i32_e32 vcc, v82, v83
	v_max3_f32 v0, v0, v6, v7
	v_max3_f32 v0, v0, v8, v9
	v_cndmask_b32_e32 v2, v2, v82, vcc
	v_lshlrev_b32_e32 v2, 2, v2
	ds_bpermute_b32 v2, v2, v0
	s_waitcnt lgkmcnt(0)
	v_max3_f32 v2, v184, v0, v2
	v_sub_f32_e32 v0, v184, v2
	v_mul_f32_e32 v0, 0x3e0293ee, v0
	v_exp_f32_e32 v0, v0
	s_nop 0
	v_cmp_neq_f32_e32 vcc, 1.0, v0
	s_cbranch_vccz .LBB0_154
	v_mul_f32_e32 v161, v161, v0
	v_pk_mul_f32 v[78:79], v[0:1], v[78:79] op_sel_hi:[0,1]
	v_pk_mul_f32 v[76:77], v[0:1], v[76:77] op_sel_hi:[0,1]
	v_pk_mul_f32 v[74:75], v[0:1], v[74:75] op_sel_hi:[0,1]
	v_pk_mul_f32 v[72:73], v[0:1], v[72:73] op_sel_hi:[0,1]
	v_pk_mul_f32 v[70:71], v[0:1], v[70:71] op_sel_hi:[0,1]
	v_pk_mul_f32 v[68:69], v[0:1], v[68:69] op_sel_hi:[0,1]
	v_pk_mul_f32 v[66:67], v[0:1], v[66:67] op_sel_hi:[0,1]
	v_pk_mul_f32 v[64:65], v[0:1], v[64:65] op_sel_hi:[0,1]
	v_pk_mul_f32 v[62:63], v[0:1], v[62:63] op_sel_hi:[0,1]
	v_pk_mul_f32 v[60:61], v[0:1], v[60:61] op_sel_hi:[0,1]
	v_pk_mul_f32 v[58:59], v[0:1], v[58:59] op_sel_hi:[0,1]
	v_pk_mul_f32 v[56:57], v[0:1], v[56:57] op_sel_hi:[0,1]
	v_pk_mul_f32 v[54:55], v[0:1], v[54:55] op_sel_hi:[0,1]
	v_pk_mul_f32 v[52:53], v[0:1], v[52:53] op_sel_hi:[0,1]
	v_pk_mul_f32 v[50:51], v[0:1], v[50:51] op_sel_hi:[0,1]
	v_pk_mul_f32 v[48:49], v[0:1], v[48:49] op_sel_hi:[0,1]
	v_pk_mul_f32 v[46:47], v[0:1], v[46:47] op_sel_hi:[0,1]
	v_pk_mul_f32 v[44:45], v[0:1], v[44:45] op_sel_hi:[0,1]
	v_pk_mul_f32 v[42:43], v[0:1], v[42:43] op_sel_hi:[0,1]
	v_pk_mul_f32 v[40:41], v[0:1], v[40:41] op_sel_hi:[0,1]
	v_pk_mul_f32 v[38:39], v[0:1], v[38:39] op_sel_hi:[0,1]
	v_pk_mul_f32 v[36:37], v[0:1], v[36:37] op_sel_hi:[0,1]
	v_pk_mul_f32 v[34:35], v[0:1], v[34:35] op_sel_hi:[0,1]
	v_pk_mul_f32 v[32:33], v[0:1], v[32:33] op_sel_hi:[0,1]
	v_pk_mul_f32 v[30:31], v[0:1], v[30:31] op_sel_hi:[0,1]
	v_pk_mul_f32 v[28:29], v[0:1], v[28:29] op_sel_hi:[0,1]
	v_pk_mul_f32 v[26:27], v[0:1], v[26:27] op_sel_hi:[0,1]
	v_pk_mul_f32 v[24:25], v[0:1], v[24:25] op_sel_hi:[0,1]
	v_pk_mul_f32 v[22:23], v[0:1], v[22:23] op_sel_hi:[0,1]
	v_pk_mul_f32 v[20:21], v[0:1], v[20:21] op_sel_hi:[0,1]
	v_pk_mul_f32 v[18:19], v[0:1], v[18:19] op_sel_hi:[0,1]
	v_pk_mul_f32 v[16:17], v[0:1], v[16:17] op_sel_hi:[0,1]
	s_branch .LBB0_154
.LBB0_159:
	s_lshl_b32 s0, s14, 6
	v_cmp_le_i32_e32 vcc, s0, v179
	s_nop 0
	s_waitcnt vmcnt(3)
	ds_write_b128 v180, v[156:159]
	s_waitcnt vmcnt(2)
	ds_write_b128 v181, v[152:155]
	s_waitcnt vmcnt(1)
	ds_write_b128 v182, v[148:151] offset:17408
	s_waitcnt vmcnt(0)
	ds_write_b128 v183, v[144:147] offset:17408
	s_waitcnt lgkmcnt(0)
	s_barrier
	s_and_saveexec_b64 s[0:1], vcc
	s_xor_b64 s[0:1], exec, s[0:1]
	s_cbranch_execz .LBB0_164
; #define MFMA32(a, b, c) __builtin_amdgcn_mfma_f32_32x32x16_bf16((a), (b), (c), 0, 0, 0)
; DI f32x16 zero16() { f32x16 z; for (int i = 0; i < 16; ++i) z[i] = 0.f; return z; }
; template <int DQK, int MODE>
; DI void attn_core(const u16* __restrict__ Qg, int ldq, const u16* __restrict__ Kg, int ldk, const u16* __restrict__ Vtg,
;                   const u64* __restrict__ maskg, int q0, float scale, char* smem, int* sflags, f32x16 (&o)[4], float& l_run) {
;     ...
;     u64 mbits = 0;
;     if (MODE == 1) mbits = maskg[(long)qrow * 64 + tau] >> (8 * hh);
;     f32x16 s[2];
;     s[0] = zero16(); s[1] = zero16();
; #pragma unroll
;     for (int kt = 0; kt < 2; ++kt)
; #pragma unroll
;       for (int ks = 0; ks < NKS; ++ks) {
;         const bf16x8 kf = *(const bf16x8*)(Ks + (32 * kt + krow) * KSTR + ks * 16 + hh * 8);
;         s[kt] = MFMA32(kf, qf[ks], s[kt]);
;       }
;     const int kbase = tau * 64 + 8 * hh;
;     if (MODE == 0 || MODE == 1) {
;       const bool need_mask = (MODE == 1) || (tau * 64 + 63 > q0 + 32 * wid);
;       float mx = -1e30f;
;       if (need_mask) {
; #pragma unroll
;         for (int kt = 0; kt < 2; ++kt)
; #pragma unroll
;           for (int i = 0; i < 16; ++i) {
;             bool valid;
;             if (MODE == 1) valid = (mbits >> (32 * kt + 16 * (i >> 3) + (i & 7))) & 1ull;
;             else valid = (kbase + 32 * kt + 16 * (i >> 3) + (i & 7)) <= qrow;
;             s[kt][i] = valid ? s[kt][i] : -1e30f;
;           }
;       }
; #pragma unroll
;       for (int kt = 0; kt < 2; ++kt)
; #pragma unroll
;         for (int i = 0; i < 16; ++i) mx = fmaxf(mx, s[kt][i]);
;       mx = fmaxf(mx, __shfl_xor(mx, 32));
	v_readlane_b32 s4, v249, 29
	v_readlane_b32 s5, v249, 30
	s_mov_b32 s15, s5
	s_add_i32 s14, s13, -2
	v_lshl_add_u64 v[2:3], s[14:15], 3, v[164:165]
	v_add_u32_e32 v0, v174, v178
	global_load_dwordx2 v[10:11], v[2:3], off offset:8
	ds_read_b128 v[12:15], v0
	ds_read_b128 v[144:147], v0 offset:32
	ds_read_b128 v[148:151], v0 offset:64
	ds_read_b128 v[152:155], v0 offset:96
	ds_read_b128 v[156:159], v0 offset:128
	ds_read_b128 v[162:165], v0 offset:160
	s_waitcnt lgkmcnt(5)
	v_mfma_f32_32x32x16_bf16 v[80:95], v[12:15], v[140:143], 0
	ds_read_b128 v[12:15], v0 offset:192
	v_writelane_b32 v249, s4, 29
	s_nop 1
	v_writelane_b32 v249, s5, 30
	s_waitcnt lgkmcnt(5)
	v_mfma_f32_32x32x16_bf16 v[80:95], v[144:147], v[136:139], v[80:95]
	ds_read_b128 v[144:147], v0 offset:224
	s_waitcnt lgkmcnt(5)
	v_mfma_f32_32x32x16_bf16 v[80:95], v[148:151], v[132:135], v[80:95]
	ds_read_b128 v[148:151], v0 offset:8704
	s_waitcnt lgkmcnt(5)
	v_mfma_f32_32x32x16_bf16 v[80:95], v[152:155], v[128:131], v[80:95]
	ds_read_b128 v[152:155], v0 offset:8736
	s_waitcnt lgkmcnt(5)
	v_mfma_f32_32x32x16_bf16 v[80:95], v[156:159], v[124:127], v[80:95]
	ds_read_b128 v[156:159], v0 offset:8768
	s_waitcnt lgkmcnt(5)
	v_mfma_f32_32x32x16_bf16 v[80:95], v[162:165], v[120:123], v[80:95]
	ds_read_b128 v[162:165], v0 offset:8800
	s_waitcnt lgkmcnt(5)
	v_mfma_f32_32x32x16_bf16 v[80:95], v[12:15], v[116:119], v[80:95]
	ds_read_b128 v[12:15], v0 offset:8832
	s_waitcnt lgkmcnt(5)
	v_mfma_f32_32x32x16_bf16 v[80:95], v[144:147], v[112:115], v[80:95]
	ds_read_b128 v[144:147], v0 offset:8864
	s_waitcnt lgkmcnt(5)
	v_mfma_f32_32x32x16_bf16 v[96:111], v[148:151], v[140:143], 0
	ds_read_b128 v[148:151], v0 offset:8896
	s_waitcnt lgkmcnt(5)
	v_mfma_f32_32x32x16_bf16 v[96:111], v[152:155], v[136:139], v[96:111]
	ds_read_b128 v[152:155], v0 offset:8928
	s_waitcnt lgkmcnt(5)
	v_mfma_f32_32x32x16_bf16 v[96:111], v[156:159], v[132:135], v[96:111]
	s_waitcnt lgkmcnt(4)
	v_mfma_f32_32x32x16_bf16 v[96:111], v[162:165], v[128:131], v[96:111]
	s_waitcnt lgkmcnt(3)
	v_mfma_f32_32x32x16_bf16 v[96:111], v[12:15], v[124:127], v[96:111]
	s_waitcnt lgkmcnt(2)
	v_mfma_f32_32x32x16_bf16 v[96:111], v[144:147], v[120:123], v[96:111]
	s_waitcnt lgkmcnt(1)
	v_mfma_f32_32x32x16_bf16 v[96:111], v[148:151], v[116:119], v[96:111]
	s_waitcnt vmcnt(0)
	v_lshrrev_b32_e32 v0, v160, v10
	v_and_b32_e32 v0, 1, v0
	v_cmp_eq_u32_e32 vcc, 1, v0
	s_nop 1
	v_cndmask_b32_e32 v121, v225, v80, vcc
	s_waitcnt lgkmcnt(0)
	v_mfma_f32_32x32x16_bf16 v[96:111], v[152:155], v[112:115], v[96:111]
	v_lshrrev_b64 v[2:3], v160, v[10:11]
	v_and_b32_e32 v0, 2, v2
	v_cmp_ne_u32_e32 vcc, 0, v0
	v_and_b32_e32 v0, 4, v2
	s_nop 0
	v_cndmask_b32_e32 v118, v225, v81, vcc
	v_cmp_ne_u32_e32 vcc, 0, v0
	v_and_b32_e32 v0, 8, v2
	s_nop 0
	v_cndmask_b32_e32 v120, v225, v82, vcc
	v_cmp_ne_u32_e32 vcc, 0, v0
	v_and_b32_e32 v0, 16, v2
	s_nop 0
	v_cndmask_b32_e32 v119, v225, v83, vcc
	v_cmp_ne_u32_e32 vcc, 0, v0
	v_and_b32_e32 v0, 32, v2
	s_nop 0
	v_cndmask_b32_e32 v122, v225, v84, vcc
	v_cmp_ne_u32_e32 vcc, 0, v0
	v_and_b32_e32 v0, 64, v2
	s_nop 0
	v_cndmask_b32_e32 v116, v225, v85, vcc
	v_cmp_ne_u32_e32 vcc, 0, v0
	v_and_b32_e32 v0, 0x80, v2
	s_nop 0
	v_cndmask_b32_e32 v117, v225, v86, vcc
	v_cmp_ne_u32_e32 vcc, 0, v0
	v_and_b32_e32 v0, 0x10000, v2
	s_nop 0
	v_cndmask_b32_e32 v115, v225, v87, vcc
	v_cmp_ne_u32_e32 vcc, 0, v0
	v_and_b32_e32 v0, 0x20000, v2
	s_nop 0
	v_cndmask_b32_e32 v85, v225, v88, vcc
	v_cmp_ne_u32_e32 vcc, 0, v0
	v_and_b32_e32 v0, 0x40000, v2
	s_nop 0
	v_cndmask_b32_e32 v87, v225, v89, vcc
	v_cmp_ne_u32_e32 vcc, 0, v0
	v_and_b32_e32 v0, 0x80000, v2
	s_nop 0
	v_cndmask_b32_e32 v88, v225, v90, vcc
	v_cmp_ne_u32_e32 vcc, 0, v0
	v_and_b32_e32 v0, 0x100000, v2
	s_nop 0
	v_cndmask_b32_e32 v91, v225, v91, vcc
	v_cmp_ne_u32_e32 vcc, 0, v0
	v_and_b32_e32 v0, 0x200000, v2
	s_nop 0
	v_cndmask_b32_e32 v92, v225, v92, vcc
	v_cmp_ne_u32_e32 vcc, 0, v0
	v_and_b32_e32 v0, 0x400000, v2
	s_nop 0
	v_cndmask_b32_e32 v13, v225, v93, vcc
	v_cmp_ne_u32_e32 vcc, 0, v0
	v_and_b32_e32 v0, 0x800000, v2
	v_mbcnt_hi_u32_b32 v2, -1, v223
	v_cndmask_b32_e32 v113, v225, v94, vcc
	v_cmp_ne_u32_e32 vcc, 0, v0
	v_and_b32_e32 v0, 1, v3
	v_and_b32_e32 v4, 64, v2
	v_cndmask_b32_e32 v14, v225, v95, vcc
	v_cmp_eq_u32_e32 vcc, 1, v0
	v_and_b32_e32 v0, 2, v3
	v_add_u32_e32 v4, 64, v4
	v_cndmask_b32_e32 v114, v225, v96, vcc
	v_cmp_ne_u32_e32 vcc, 0, v0
	v_and_b32_e32 v0, 4, v3
	s_nop 0
	v_cndmask_b32_e32 v112, v225, v97, vcc
	v_cmp_ne_u32_e32 vcc, 0, v0
	v_and_b32_e32 v0, 8, v3
	s_nop 0
	v_cndmask_b32_e32 v15, v225, v98, vcc
	v_cmp_ne_u32_e32 vcc, 0, v0
	v_and_b32_e32 v0, 16, v3
	s_nop 0
	v_cndmask_b32_e32 v80, v225, v99, vcc
	v_cmp_ne_u32_e32 vcc, 0, v0
	v_and_b32_e32 v0, 32, v3
	s_nop 0
	v_cndmask_b32_e32 v81, v225, v100, vcc
	v_cmp_ne_u32_e32 vcc, 0, v0
	v_and_b32_e32 v0, 64, v3
	s_nop 0
	v_cndmask_b32_e32 v82, v225, v101, vcc
	v_cmp_ne_u32_e32 vcc, 0, v0
	v_and_b32_e32 v0, 0x80, v3
	s_nop 0
	v_cndmask_b32_e32 v83, v225, v102, vcc
	v_cmp_ne_u32_e32 vcc, 0, v0
	v_and_b32_e32 v0, 0x10000, v3
	s_nop 0
	v_cndmask_b32_e32 v84, v225, v103, vcc
	v_cmp_ne_u32_e32 vcc, 0, v0
	v_and_b32_e32 v0, 0x20000, v3
	s_nop 0
	v_cndmask_b32_e32 v5, v225, v104, vcc
	v_cmp_ne_u32_e32 vcc, 0, v0
	v_and_b32_e32 v0, 0x40000, v3
	s_nop 0
	v_cndmask_b32_e32 v6, v225, v105, vcc
	v_cmp_ne_u32_e32 vcc, 0, v0
	v_and_b32_e32 v0, 0x80000, v3
	s_nop 0
	v_cndmask_b32_e32 v7, v225, v106, vcc
	v_cmp_ne_u32_e32 vcc, 0, v0
	v_and_b32_e32 v0, 0x100000, v3
	s_nop 0
	v_cndmask_b32_e32 v8, v225, v107, vcc
	v_cmp_ne_u32_e32 vcc, 0, v0
	v_and_b32_e32 v0, 0x200000, v3
	s_nop 0
	v_cndmask_b32_e32 v9, v225, v108, vcc
	v_cmp_ne_u32_e32 vcc, 0, v0
	v_and_b32_e32 v0, 0x400000, v3
	s_nop 0
	v_cndmask_b32_e32 v10, v225, v109, vcc
	v_cmp_ne_u32_e32 vcc, 0, v0
	v_and_b32_e32 v0, 0x800000, v3
	v_xor_b32_e32 v3, 32, v2
	v_cndmask_b32_e32 v11, v225, v110, vcc
	v_cmp_ne_u32_e32 vcc, 0, v0
	v_max3_f32 v0, v121, s58, v118
	v_max3_f32 v0, v0, v120, v119
	v_max3_f32 v0, v0, v122, v116
	v_max3_f32 v0, v0, v117, v115
	v_max3_f32 v0, v0, v85, v87
	v_max3_f32 v0, v0, v88, v91
	v_max3_f32 v0, v0, v92, v13
	v_max3_f32 v0, v0, v113, v14
	v_max3_f32 v0, v0, v114, v112
	v_max3_f32 v0, v0, v15, v80
	v_max3_f32 v0, v0, v81, v82
	v_max3_f32 v0, v0, v83, v84
	v_max3_f32 v0, v0, v5, v6
	v_cndmask_b32_e32 v12, v225, v111, vcc
	v_max3_f32 v0, v0, v7, v8
	v_cmp_lt_i32_e32 vcc, v3, v4
	v_max3_f32 v0, v0, v9, v10
	v_max3_f32 v0, v0, v11, v12
	v_cndmask_b32_e32 v86, v2, v3, vcc
	v_lshlrev_b32_e32 v86, 2, v86
	ds_bpermute_b32 v86, v86, v0
	s_waitcnt lgkmcnt(0)
	v_max3_f32 v86, v184, v0, v86
	v_sub_f32_e32 v0, v184, v86
	v_mul_f32_e32 v0, 0x3e0293ee, v0
	v_exp_f32_e32 v0, v0
	s_nop 0
	v_cmp_neq_f32_e32 vcc, 1.0, v0
	s_cbranch_vccz .LBB0_162
; template <int DQK, int MODE>
; DI void attn_core(const u16* __restrict__ Qg, int ldq, const u16* __restrict__ Kg, int ldk, const u16* __restrict__ Vtg,
;                   const u64* __restrict__ maskg, int q0, float scale, char* smem, int* sflags, f32x16 (&o)[4], float& l_run) {
;     ...
;       if (__any(alpha != 1.0f)) {
;         l_run *= alpha;
; #pragma unroll
;         for (int t = 0; t < 4; ++t)
; #pragma unroll
;           for (int i = 0; i < 16; ++i) o[t][i] *= alpha;
;       }
	v_mul_f32_e32 v101, v161, v0
	v_pk_mul_f32 v[78:79], v[0:1], v[78:79] op_sel_hi:[0,1]
	v_pk_mul_f32 v[76:77], v[0:1], v[76:77] op_sel_hi:[0,1]
	v_pk_mul_f32 v[74:75], v[0:1], v[74:75] op_sel_hi:[0,1]
	v_pk_mul_f32 v[72:73], v[0:1], v[72:73] op_sel_hi:[0,1]
	v_pk_mul_f32 v[70:71], v[0:1], v[70:71] op_sel_hi:[0,1]
	v_pk_mul_f32 v[68:69], v[0:1], v[68:69] op_sel_hi:[0,1]
	v_pk_mul_f32 v[66:67], v[0:1], v[66:67] op_sel_hi:[0,1]
	v_pk_mul_f32 v[64:65], v[0:1], v[64:65] op_sel_hi:[0,1]
	v_pk_mul_f32 v[62:63], v[0:1], v[62:63] op_sel_hi:[0,1]
	v_pk_mul_f32 v[60:61], v[0:1], v[60:61] op_sel_hi:[0,1]
	v_pk_mul_f32 v[58:59], v[0:1], v[58:59] op_sel_hi:[0,1]
	v_pk_mul_f32 v[56:57], v[0:1], v[56:57] op_sel_hi:[0,1]
	v_pk_mul_f32 v[54:55], v[0:1], v[54:55] op_sel_hi:[0,1]
	v_pk_mul_f32 v[52:53], v[0:1], v[52:53] op_sel_hi:[0,1]
	v_pk_mul_f32 v[50:51], v[0:1], v[50:51] op_sel_hi:[0,1]
	v_pk_mul_f32 v[48:49], v[0:1], v[48:49] op_sel_hi:[0,1]
	v_pk_mul_f32 v[46:47], v[0:1], v[46:47] op_sel_hi:[0,1]
	v_pk_mul_f32 v[44:45], v[0:1], v[44:45] op_sel_hi:[0,1]
	v_pk_mul_f32 v[42:43], v[0:1], v[42:43] op_sel_hi:[0,1]
	v_pk_mul_f32 v[40:41], v[0:1], v[40:41] op_sel_hi:[0,1]
	v_pk_mul_f32 v[38:39], v[0:1], v[38:39] op_sel_hi:[0,1]
	v_pk_mul_f32 v[36:37], v[0:1], v[36:37] op_sel_hi:[0,1]
	v_pk_mul_f32 v[34:35], v[0:1], v[34:35] op_sel_hi:[0,1]
	v_pk_mul_f32 v[32:33], v[0:1], v[32:33] op_sel_hi:[0,1]
	v_pk_mul_f32 v[30:31], v[0:1], v[30:31] op_sel_hi:[0,1]
	v_pk_mul_f32 v[28:29], v[0:1], v[28:29] op_sel_hi:[0,1]
	v_pk_mul_f32 v[26:27], v[0:1], v[26:27] op_sel_hi:[0,1]
	v_pk_mul_f32 v[24:25], v[0:1], v[24:25] op_sel_hi:[0,1]
	v_pk_mul_f32 v[22:23], v[0:1], v[22:23] op_sel_hi:[0,1]
	v_pk_mul_f32 v[20:21], v[0:1], v[20:21] op_sel_hi:[0,1]
	v_pk_mul_f32 v[18:19], v[0:1], v[18:19] op_sel_hi:[0,1]
	v_pk_mul_f32 v[16:17], v[0:1], v[16:17] op_sel_hi:[0,1]
	s_branch .LBB0_163

; #define MFMA32(a, b, c) __builtin_amdgcn_mfma_f32_32x32x16_bf16((a), (b), (c), 0, 0, 0)
; DI f32x16 zero16() { f32x16 z; for (int i = 0; i < 16; ++i) z[i] = 0.f; return z; }
; template <int DQK, int MODE>
; DI void attn_core(const u16* __restrict__ Qg, int ldq, const u16* __restrict__ Kg, int ldk, const u16* __restrict__ Vtg,
;                   const u64* __restrict__ maskg, int q0, float scale, char* smem, int* sflags, f32x16 (&o)[4], float& l_run) {
;     ...
;   for (int it = 0; it < ntiles; ++it, tau += step) {
;     __syncthreads();
;     if (MODE == 2 && it > 0) {
;       if (!(sflags[0] | sflags[1] | sflags[2] | sflags[3] | sflags[4] | sflags[5] | sflags[6] | sflags[7])) break;
;     }
;     if (MODE == 2) gload(tau);
; #pragma unroll
;     for (int i = 0; i < NVK; ++i) {
;       const int v = tid + NT * i, row = v / VPR, c = v % VPR;
;       *(u32x4*)(Ks + row * KSTR + c * 8) = rk[i];
;     }
; #pragma unroll
;     for (int i = 0; i < 2; ++i) {
;       const int v = tid + NT * i, row = v >> 3, c = v & 7;
;       *(u32x4*)(Vs + row * 72 + c * 8) = rv[i];
;     }
;     __syncthreads();
;     if (MODE != 2 && it + 1 < ntiles) gload(tau + step);
;     if (tau * 64 > q0 + 32 * wid + 31) {
;       if (MODE == 2 && lane == 0) sflags[wid] = 1;
;       continue;
;     }
;     u64 mbits = 0;
;     if (MODE == 1) mbits = maskg[(long)qrow * 64 + tau] >> (8 * hh);
;     f32x16 s[2];
;     s[0] = zero16(); s[1] = zero16();
; #pragma unroll
;     for (int kt = 0; kt < 2; ++kt)
; #pragma unroll
;       for (int ks = 0; ks < NKS; ++ks) {
;         const bf16x8 kf = *(const bf16x8*)(Ks + (32 * kt + krow) * KSTR + ks * 16 + hh * 8);
;         s[kt] = MFMA32(kf, qf[ks], s[kt]);
;       }
.LBB0_169:
	v_add_u32_e32 v0, s14, v220
	v_mad_i64_i32 v[2:3], s[4:5], v0, s95, v[184:185]
	v_add_u32_e32 v0, s14, v219
	s_add_i32 s0, s14, 64
	v_mad_i64_i32 v[4:5], s[4:5], v0, s95, v[186:187]
	v_add_u32_e32 v0, s14, v218
	s_nop 0
	s_waitcnt vmcnt(0)
	ds_write_b128 v221, v[176:179]
	ds_write_b128 v226, v[172:175]
	ds_write_b128 v227, v[168:171]
	ds_write_b128 v228, v[164:167] offset:25600
	ds_write_b128 v229, v[160:163] offset:25600
	s_waitcnt lgkmcnt(0)
	s_barrier
	global_load_dwordx4 v[176:179], v[2:3], off
	global_load_dwordx4 v[172:175], v[4:5], off
	v_mad_i64_i32 v[2:3], s[4:5], v0, s95, v[206:207]
	s_ashr_i32 s1, s0, 31
	s_lshl_b64 s[4:5], s[0:1], 1
	global_load_dwordx4 v[168:171], v[2:3], off
	v_lshl_add_u64 v[2:3], v[180:181], 0, s[4:5]
	v_lshl_add_u64 v[4:5], v[182:183], 0, s[4:5]
	global_load_dwordx4 v[164:167], v[2:3], off
	global_load_dwordx4 v[160:163], v[4:5], off
	v_cmp_le_i32_e32 vcc, s14, v217
	s_and_saveexec_b64 s[4:5], vcc
	s_cbranch_execz .LBB0_175
	v_add_u32_e32 v0, v211, v216
	ds_read_b128 v[10:13], v0
	ds_read_b128 v[198:201], v0 offset:32
	ds_read_b128 v[202:205], v0 offset:64
	ds_read_b128 v[232:235], v0 offset:96
	ds_read_b128 v[236:239], v0 offset:128
	ds_read_b128 v[240:243], v0 offset:160
	s_add_i32 s1, s14, 63
	v_cmp_gt_i32_e32 vcc, s1, v214
	s_waitcnt lgkmcnt(5)
	v_mfma_f32_32x32x16_bf16 v[80:95], v[10:13], v[156:159], 0
	ds_read_b128 v[10:13], v0 offset:192
	s_waitcnt lgkmcnt(5)
	v_mfma_f32_32x32x16_bf16 v[80:95], v[198:201], v[152:155], v[80:95]
	ds_read_b128 v[198:201], v0 offset:224
	s_waitcnt lgkmcnt(5)
	v_mfma_f32_32x32x16_bf16 v[80:95], v[202:205], v[148:151], v[80:95]
	ds_read_b128 v[202:205], v0 offset:256
	s_waitcnt lgkmcnt(5)
	v_mfma_f32_32x32x16_bf16 v[80:95], v[232:235], v[144:147], v[80:95]
	ds_read_b128 v[232:235], v0 offset:288
	s_waitcnt lgkmcnt(5)
	v_mfma_f32_32x32x16_bf16 v[80:95], v[236:239], v[140:143], v[80:95]
	ds_read_b128 v[236:239], v0 offset:320
	s_waitcnt lgkmcnt(5)
	v_mfma_f32_32x32x16_bf16 v[80:95], v[240:243], v[136:139], v[80:95]
	ds_read_b128 v[240:243], v0 offset:352
	s_waitcnt lgkmcnt(5)
	v_mfma_f32_32x32x16_bf16 v[80:95], v[10:13], v[132:135], v[80:95]
	ds_read_b128 v[10:13], v0 offset:12800
	s_waitcnt lgkmcnt(5)
	v_mfma_f32_32x32x16_bf16 v[80:95], v[198:201], v[128:131], v[80:95]
	ds_read_b128 v[198:201], v0 offset:12832
	s_waitcnt lgkmcnt(5)
	v_mfma_f32_32x32x16_bf16 v[80:95], v[202:205], v[124:127], v[80:95]
	ds_read_b128 v[202:205], v0 offset:12864
	s_waitcnt lgkmcnt(5)
	v_mfma_f32_32x32x16_bf16 v[80:95], v[232:235], v[120:123], v[80:95]
	ds_read_b128 v[232:235], v0 offset:12896
	s_waitcnt lgkmcnt(5)
	v_mfma_f32_32x32x16_bf16 v[80:95], v[236:239], v[116:119], v[80:95]
	ds_read_b128 v[236:239], v0 offset:12928
	s_waitcnt lgkmcnt(5)
	v_mfma_f32_32x32x16_bf16 v[80:95], v[240:243], v[112:115], v[80:95]
	ds_read_b128 v[240:243], v0 offset:12960
	s_waitcnt lgkmcnt(5)
	v_mfma_f32_32x32x16_bf16 v[96:111], v[10:13], v[156:159], 0
	ds_read_b128 v[10:13], v0 offset:12992
	s_waitcnt lgkmcnt(5)
	v_mfma_f32_32x32x16_bf16 v[96:111], v[198:201], v[152:155], v[96:111]
	ds_read_b128 v[198:201], v0 offset:13024
	s_waitcnt lgkmcnt(5)
	v_mfma_f32_32x32x16_bf16 v[96:111], v[202:205], v[148:151], v[96:111]
	ds_read_b128 v[202:205], v0 offset:13056
	s_waitcnt lgkmcnt(5)
	v_mfma_f32_32x32x16_bf16 v[96:111], v[232:235], v[144:147], v[96:111]
	ds_read_b128 v[232:235], v0 offset:13088
	s_waitcnt lgkmcnt(5)
	v_mfma_f32_32x32x16_bf16 v[96:111], v[236:239], v[140:143], v[96:111]
	ds_read_b128 v[236:239], v0 offset:13120
	s_waitcnt lgkmcnt(5)
	v_mfma_f32_32x32x16_bf16 v[96:111], v[240:243], v[136:139], v[96:111]
	ds_read_b128 v[240:243], v0 offset:13152
	s_waitcnt lgkmcnt(5)
	v_mfma_f32_32x32x16_bf16 v[96:111], v[10:13], v[132:135], v[96:111]
	s_waitcnt lgkmcnt(4)
	v_mfma_f32_32x32x16_bf16 v[96:111], v[198:201], v[128:131], v[96:111]
	s_waitcnt lgkmcnt(3)
	v_mfma_f32_32x32x16_bf16 v[96:111], v[202:205], v[124:127], v[96:111]
	s_waitcnt lgkmcnt(2)
	v_mfma_f32_32x32x16_bf16 v[96:111], v[232:235], v[120:123], v[96:111]
	s_waitcnt lgkmcnt(1)
	v_mfma_f32_32x32x16_bf16 v[96:111], v[236:239], v[116:119], v[96:111]
	s_waitcnt lgkmcnt(0)
	v_mfma_f32_32x32x16_bf16 v[96:111], v[240:243], v[112:115], v[96:111]
	s_and_saveexec_b64 s[6:7], vcc
	s_cbranch_execz .LBB0_172
; template <int DQK, int MODE>
; DI void attn_core(const u16* __restrict__ Qg, int ldq, const u16* __restrict__ Kg, int ldk, const u16* __restrict__ Vtg,
;                   const u64* __restrict__ maskg, int q0, float scale, char* smem, int* sflags, f32x16 (&o)[4], float& l_run) {
;     ...
;       const bool need_mask = (MODE == 1) || (tau * 64 + 63 > q0 + 32 * wid);
;       float mx = -1e30f;
;       if (need_mask) {
; #pragma unroll
;         for (int kt = 0; kt < 2; ++kt)
; #pragma unroll
;           for (int i = 0; i < 16; ++i) {
;             bool valid;
;             if (MODE == 1) valid = (mbits >> (32 * kt + 16 * (i >> 3) + (i & 7))) & 1ull;
;             else valid = (kbase + 32 * kt + 16 * (i >> 3) + (i & 7)) <= qrow;
;             s[kt][i] = valid ? s[kt][i] : -1e30f;
;           }
	v_add_u32_e32 v0, s14, v215
	v_cmp_le_i32_e32 vcc, v0, v213
	v_add_u32_e32 v2, 2, v0
	s_nop 0
	v_cndmask_b32_e32 v80, v225, v80, vcc
	v_cmp_lt_i32_e32 vcc, v0, v213
	s_nop 1
	v_cndmask_b32_e32 v81, v225, v81, vcc
	v_cmp_le_i32_e32 vcc, v2, v213
	v_add_u32_e32 v2, 3, v0
	s_nop 0
	v_cndmask_b32_e32 v82, v225, v82, vcc
	v_cmp_le_i32_e32 vcc, v2, v213
	v_add_u32_e32 v2, 4, v0
	s_nop 0
	v_cndmask_b32_e32 v83, v225, v83, vcc
	v_cmp_le_i32_e32 vcc, v2, v213
	v_add_u32_e32 v2, 5, v0
	s_nop 0
	v_cndmask_b32_e32 v84, v225, v84, vcc
	v_cmp_le_i32_e32 vcc, v2, v213
	v_add_u32_e32 v2, 6, v0
	s_nop 0
	v_cndmask_b32_e32 v85, v225, v85, vcc
	v_cmp_le_i32_e32 vcc, v2, v213
	v_add_u32_e32 v2, 7, v0
	s_nop 0
	v_cndmask_b32_e32 v86, v225, v86, vcc
	v_cmp_le_i32_e32 vcc, v2, v213
	v_add_u32_e32 v2, 16, v0
	s_nop 0
	v_cndmask_b32_e32 v87, v225, v87, vcc
	v_cmp_le_i32_e32 vcc, v2, v213
	v_add_u32_e32 v2, 17, v0
	s_nop 0
	v_cndmask_b32_e32 v88, v225, v88, vcc
	v_cmp_le_i32_e32 vcc, v2, v213
	v_add_u32_e32 v2, 18, v0
	s_nop 0
	v_cndmask_b32_e32 v89, v225, v89, vcc
	v_cmp_le_i32_e32 vcc, v2, v213
	v_add_u32_e32 v2, 19, v0
	s_nop 0
	v_cndmask_b32_e32 v90, v225, v90, vcc
	v_cmp_le_i32_e32 vcc, v2, v213
	v_add_u32_e32 v2, 20, v0
	s_nop 0
	v_cndmask_b32_e32 v91, v225, v91, vcc
	v_cmp_le_i32_e32 vcc, v2, v213
	v_add_u32_e32 v2, 21, v0
	s_nop 0
	v_cndmask_b32_e32 v92, v225, v92, vcc
	v_cmp_le_i32_e32 vcc, v2, v213
	v_add_u32_e32 v2, 22, v0
	s_nop 0
	v_cndmask_b32_e32 v93, v225, v93, vcc
	v_cmp_le_i32_e32 vcc, v2, v213
	v_add_u32_e32 v2, 23, v0
	s_nop 0
	v_cndmask_b32_e32 v94, v225, v94, vcc
	v_cmp_le_i32_e32 vcc, v2, v213
	v_add_u32_e32 v2, 32, v0
	s_nop 0
	v_cndmask_b32_e32 v95, v225, v95, vcc
	v_cmp_le_i32_e32 vcc, v2, v213
	v_add_u32_e32 v2, 33, v0
	s_nop 0
	v_cndmask_b32_e32 v96, v225, v96, vcc
	v_cmp_le_i32_e32 vcc, v2, v213
	v_add_u32_e32 v2, 34, v0
	s_nop 0
	v_cndmask_b32_e32 v97, v225, v97, vcc
	v_cmp_le_i32_e32 vcc, v2, v213
	v_add_u32_e32 v2, 35, v0
	s_nop 0
	v_cndmask_b32_e32 v98, v225, v98, vcc
	v_cmp_le_i32_e32 vcc, v2, v213
	v_add_u32_e32 v2, 36, v0
	s_nop 0
	v_cndmask_b32_e32 v99, v225, v99, vcc
	v_cmp_le_i32_e32 vcc, v2, v213
	v_add_u32_e32 v2, 37, v0
	s_nop 0
	v_cndmask_b32_e32 v100, v225, v100, vcc
	v_cmp_le_i32_e32 vcc, v2, v213
	v_add_u32_e32 v2, 38, v0
	s_nop 0
	v_cndmask_b32_e32 v101, v225, v101, vcc
	v_cmp_le_i32_e32 vcc, v2, v213
	v_add_u32_e32 v2, 39, v0
	s_nop 0
	v_cndmask_b32_e32 v102, v225, v102, vcc
	v_cmp_le_i32_e32 vcc, v2, v213
	v_add_u32_e32 v2, 48, v0
	s_nop 0
	v_cndmask_b32_e32 v103, v225, v103, vcc
	v_cmp_le_i32_e32 vcc, v2, v213
	v_add_u32_e32 v2, 49, v0
	s_nop 0
	v_cndmask_b32_e32 v104, v225, v104, vcc
	v_cmp_le_i32_e32 vcc, v2, v213
	v_add_u32_e32 v2, 50, v0
	s_nop 0
	v_cndmask_b32_e32 v105, v225, v105, vcc
	v_cmp_le_i32_e32 vcc, v2, v213
	v_add_u32_e32 v2, 51, v0
	s_nop 0
	v_cndmask_b32_e32 v106, v225, v106, vcc
	v_cmp_le_i32_e32 vcc, v2, v213
	v_add_u32_e32 v2, 52, v0
	s_nop 0
	v_cndmask_b32_e32 v107, v225, v107, vcc
	v_cmp_le_i32_e32 vcc, v2, v213
	v_add_u32_e32 v2, 53, v0
	s_nop 0
	v_cndmask_b32_e32 v108, v225, v108, vcc
	v_cmp_le_i32_e32 vcc, v2, v213
	v_add_u32_e32 v2, 54, v0
	v_add_u32_e32 v0, 55, v0
	v_cndmask_b32_e32 v109, v225, v109, vcc
	v_cmp_le_i32_e32 vcc, v2, v213
	s_nop 1
	v_cndmask_b32_e32 v110, v225, v110, vcc
	v_cmp_le_i32_e32 vcc, v0, v213
	s_nop 1
	v_cndmask_b32_e32 v111, v225, v111, vcc

; #define MFMA32(a, b, c) __builtin_amdgcn_mfma_f32_32x32x16_bf16((a), (b), (c), 0, 0, 0)
; DI f32x16 zero16() { f32x16 z; for (int i = 0; i < 16; ++i) z[i] = 0.f; return z; }
; template <int DQK, int MODE>
; DI void attn_core(const u16* __restrict__ Qg, int ldq, const u16* __restrict__ Kg, int ldk, const u16* __restrict__ Vtg,
;                   const u64* __restrict__ maskg, int q0, float scale, char* smem, int* sflags, f32x16 (&o)[4], float& l_run) {
;     ...
;   for (int it = 0; it < ntiles; ++it, tau += step) {
;     __syncthreads();
;     if (MODE == 2 && it > 0) {
;       if (!(sflags[0] | sflags[1] | sflags[2] | sflags[3] | sflags[4] | sflags[5] | sflags[6] | sflags[7])) break;
;     }
;     if (MODE == 2) gload(tau);
; #pragma unroll
;     for (int i = 0; i < NVK; ++i) {
;       const int v = tid + NT * i, row = v / VPR, c = v % VPR;
;       *(u32x4*)(Ks + row * KSTR + c * 8) = rk[i];
;     }
; #pragma unroll
;     for (int i = 0; i < 2; ++i) {
;       const int v = tid + NT * i, row = v >> 3, c = v & 7;
;       *(u32x4*)(Vs + row * 72 + c * 8) = rv[i];
;     }
;     __syncthreads();
;     if (MODE != 2 && it + 1 < ntiles) gload(tau + step);
;     if (tau * 64 > q0 + 32 * wid + 31) {
;       if (MODE == 2 && lane == 0) sflags[wid] = 1;
;       continue;
;     }
;     u64 mbits = 0;
;     if (MODE == 1) mbits = maskg[(long)qrow * 64 + tau] >> (8 * hh);
;     f32x16 s[2];
;     s[0] = zero16(); s[1] = zero16();
; #pragma unroll
;     for (int kt = 0; kt < 2; ++kt)
; #pragma unroll
;       for (int ks = 0; ks < NKS; ++ks) {
;         const bf16x8 kf = *(const bf16x8*)(Ks + (32 * kt + krow) * KSTR + ks * 16 + hh * 8);
;         s[kt] = MFMA32(kf, qf[ks], s[kt]);
;       }
.LBB0_175:
	s_or_b64 exec, exec, s[4:5]
	v_xor_b32_e32 v221, 0x10000, v221
	v_xor_b32_e32 v226, 0x10000, v226
	v_xor_b32_e32 v227, 0x10000, v227
	v_xor_b32_e32 v228, 0x10000, v228
	v_xor_b32_e32 v229, 0x10000, v229
	v_xor_b32_e32 v211, 0x10000, v211
	s_add_i32 s13, s13, 1
	s_cmp_eq_u32 s12, s13
	s_cbranch_scc1 .LBB0_177
	s_mov_b32 s14, s0
	s_branch .LBB0_169
.LBB0_177:
	s_lshl_b32 s6, s12, 6
	v_cmp_le_i32_e32 vcc, s6, v217
	s_nop 0
	s_waitcnt vmcnt(4)
	ds_write_b128 v221, v[176:179]
	s_waitcnt vmcnt(3)
	ds_write_b128 v226, v[172:175]
	s_waitcnt vmcnt(2)
	ds_write_b128 v227, v[168:171]
	s_waitcnt vmcnt(1)
	ds_write_b128 v228, v[164:167] offset:25600
	s_waitcnt vmcnt(0)
	ds_write_b128 v229, v[160:163] offset:25600
	s_waitcnt lgkmcnt(0)
	s_barrier
	s_and_saveexec_b64 s[0:1], vcc
	s_xor_b64 s[0:1], exec, s[0:1]
	s_cbranch_execz .LBB0_184
	v_add_u32_e32 v0, v211, v216
	ds_read_b128 v[10:13], v0
	ds_read_b128 v[160:163], v0 offset:32
	ds_read_b128 v[164:167], v0 offset:64
	ds_read_b128 v[168:171], v0 offset:96
	ds_read_b128 v[172:175], v0 offset:128
	ds_read_b128 v[176:179], v0 offset:160
	s_or_b32 s4, s6, 63
	v_cmp_gt_i32_e32 vcc, s4, v214
	s_waitcnt lgkmcnt(5)
	v_mfma_f32_32x32x16_bf16 v[80:95], v[10:13], v[156:159], 0
	ds_read_b128 v[10:13], v0 offset:192
	s_waitcnt lgkmcnt(5)
	v_mfma_f32_32x32x16_bf16 v[80:95], v[160:163], v[152:155], v[80:95]
	ds_read_b128 v[160:163], v0 offset:224
	s_waitcnt lgkmcnt(5)
	v_mfma_f32_32x32x16_bf16 v[80:95], v[164:167], v[148:151], v[80:95]
	ds_read_b128 v[164:167], v0 offset:256
	s_waitcnt lgkmcnt(5)
	v_mfma_f32_32x32x16_bf16 v[80:95], v[168:171], v[144:147], v[80:95]
	ds_read_b128 v[168:171], v0 offset:288
	s_waitcnt lgkmcnt(5)
	v_mfma_f32_32x32x16_bf16 v[80:95], v[172:175], v[140:143], v[80:95]
	ds_read_b128 v[172:175], v0 offset:320
	s_waitcnt lgkmcnt(5)
	v_mfma_f32_32x32x16_bf16 v[80:95], v[176:179], v[136:139], v[80:95]
	ds_read_b128 v[176:179], v0 offset:352
	s_waitcnt lgkmcnt(5)
	v_mfma_f32_32x32x16_bf16 v[80:95], v[10:13], v[132:135], v[80:95]
	ds_read_b128 v[10:13], v0 offset:12800
	s_waitcnt lgkmcnt(5)
	v_mfma_f32_32x32x16_bf16 v[80:95], v[160:163], v[128:131], v[80:95]
	ds_read_b128 v[160:163], v0 offset:12832
	s_waitcnt lgkmcnt(5)
	v_mfma_f32_32x32x16_bf16 v[80:95], v[164:167], v[124:127], v[80:95]
	ds_read_b128 v[164:167], v0 offset:12864
	s_waitcnt lgkmcnt(5)
	v_mfma_f32_32x32x16_bf16 v[80:95], v[168:171], v[120:123], v[80:95]
	ds_read_b128 v[168:171], v0 offset:12896
	s_waitcnt lgkmcnt(5)
	v_mfma_f32_32x32x16_bf16 v[80:95], v[172:175], v[116:119], v[80:95]
	ds_read_b128 v[172:175], v0 offset:12928
	s_waitcnt lgkmcnt(5)
	v_mfma_f32_32x32x16_bf16 v[80:95], v[176:179], v[112:115], v[80:95]
	ds_read_b128 v[176:179], v0 offset:12960
	s_waitcnt lgkmcnt(5)
	v_mfma_f32_32x32x16_bf16 v[96:111], v[10:13], v[156:159], 0
	ds_read_b128 v[10:13], v0 offset:12992
	s_waitcnt lgkmcnt(5)
	v_mfma_f32_32x32x16_bf16 v[96:111], v[160:163], v[152:155], v[96:111]
	ds_read_b128 v[160:163], v0 offset:13024
	s_waitcnt lgkmcnt(5)
	v_mfma_f32_32x32x16_bf16 v[96:111], v[164:167], v[148:151], v[96:111]
	ds_read_b128 v[164:167], v0 offset:13056
	s_waitcnt lgkmcnt(5)
	v_mfma_f32_32x32x16_bf16 v[96:111], v[168:171], v[144:147], v[96:111]
	ds_read_b128 v[168:171], v0 offset:13088
	s_waitcnt lgkmcnt(5)
	v_mfma_f32_32x32x16_bf16 v[96:111], v[172:175], v[140:143], v[96:111]
	ds_read_b128 v[172:175], v0 offset:13120
	s_waitcnt lgkmcnt(5)
	v_mfma_f32_32x32x16_bf16 v[96:111], v[176:179], v[136:139], v[96:111]
	ds_read_b128 v[176:179], v0 offset:13152
	s_waitcnt lgkmcnt(5)
	v_mfma_f32_32x32x16_bf16 v[96:111], v[10:13], v[132:135], v[96:111]
	s_waitcnt lgkmcnt(4)
	v_mfma_f32_32x32x16_bf16 v[96:111], v[160:163], v[128:131], v[96:111]
	s_waitcnt lgkmcnt(3)
	v_mfma_f32_32x32x16_bf16 v[96:111], v[164:167], v[124:127], v[96:111]
	s_waitcnt lgkmcnt(2)
	v_mfma_f32_32x32x16_bf16 v[96:111], v[168:171], v[120:123], v[96:111]
	s_waitcnt lgkmcnt(1)
	v_mfma_f32_32x32x16_bf16 v[96:111], v[172:175], v[116:119], v[96:111]
	s_waitcnt lgkmcnt(0)
	v_mfma_f32_32x32x16_bf16 v[96:111], v[176:179], v[112:115], v[96:111]
	s_and_saveexec_b64 s[4:5], vcc
	s_cbranch_execz .LBB0_180
; template <int DQK, int MODE>
; DI void attn_core(const u16* __restrict__ Qg, int ldq, const u16* __restrict__ Kg, int ldk, const u16* __restrict__ Vtg,
;                   const u64* __restrict__ maskg, int q0, float scale, char* smem, int* sflags, f32x16 (&o)[4], float& l_run) {
;     ...
;       const bool need_mask = (MODE == 1) || (tau * 64 + 63 > q0 + 32 * wid);
;       float mx = -1e30f;
;       if (need_mask) {
; #pragma unroll
;         for (int kt = 0; kt < 2; ++kt)
; #pragma unroll
;           for (int i = 0; i < 16; ++i) {
;             bool valid;
;             if (MODE == 1) valid = (mbits >> (32 * kt + 16 * (i >> 3) + (i & 7))) & 1ull;
;             else valid = (kbase + 32 * kt + 16 * (i >> 3) + (i & 7)) <= qrow;
;             s[kt][i] = valid ? s[kt][i] : -1e30f;
;           }
	v_or_b32_e32 v0, s6, v215
	v_cmp_le_i32_e32 vcc, v0, v213
	v_or_b32_e32 v2, 2, v0
	s_nop 0
	v_cndmask_b32_e32 v80, v225, v80, vcc
	v_cmp_lt_i32_e32 vcc, v0, v213
	s_nop 1
	v_cndmask_b32_e32 v81, v225, v81, vcc
	v_cmp_le_i32_e32 vcc, v2, v213
	v_or_b32_e32 v2, 3, v0
	s_nop 0
	v_cndmask_b32_e32 v82, v225, v82, vcc
	v_cmp_le_i32_e32 vcc, v2, v213
	v_or_b32_e32 v2, 4, v0
	s_nop 0
	v_cndmask_b32_e32 v83, v225, v83, vcc
	v_cmp_le_i32_e32 vcc, v2, v213
	v_or_b32_e32 v2, 5, v0
	s_nop 0
	v_cndmask_b32_e32 v84, v225, v84, vcc
	v_cmp_le_i32_e32 vcc, v2, v213
	v_or_b32_e32 v2, 6, v0
	s_nop 0
	v_cndmask_b32_e32 v85, v225, v85, vcc
	v_cmp_le_i32_e32 vcc, v2, v213
	v_or_b32_e32 v2, 7, v0
	s_nop 0
	v_cndmask_b32_e32 v86, v225, v86, vcc
	v_cmp_le_i32_e32 vcc, v2, v213
	v_or_b32_e32 v2, 16, v0
	s_nop 0
	v_cndmask_b32_e32 v87, v225, v87, vcc
	v_cmp_le_i32_e32 vcc, v2, v213
	v_or_b32_e32 v2, 17, v0
	s_nop 0
	v_cndmask_b32_e32 v88, v225, v88, vcc
	v_cmp_le_i32_e32 vcc, v2, v213
	v_or_b32_e32 v2, 18, v0
	s_nop 0
	v_cndmask_b32_e32 v89, v225, v89, vcc
	v_cmp_le_i32_e32 vcc, v2, v213
	v_or_b32_e32 v2, 19, v0
	s_nop 0
	v_cndmask_b32_e32 v90, v225, v90, vcc
	v_cmp_le_i32_e32 vcc, v2, v213
	v_or_b32_e32 v2, 20, v0
	s_nop 0
	v_cndmask_b32_e32 v91, v225, v91, vcc
	v_cmp_le_i32_e32 vcc, v2, v213
	v_or_b32_e32 v2, 21, v0
	s_nop 0
	v_cndmask_b32_e32 v92, v225, v92, vcc
	v_cmp_le_i32_e32 vcc, v2, v213
	v_or_b32_e32 v2, 22, v0
	s_nop 0
	v_cndmask_b32_e32 v93, v225, v93, vcc
	v_cmp_le_i32_e32 vcc, v2, v213
	v_or_b32_e32 v2, 23, v0
	s_nop 0
	v_cndmask_b32_e32 v94, v225, v94, vcc
	v_cmp_le_i32_e32 vcc, v2, v213
	v_or_b32_e32 v2, 32, v0
	s_nop 0
	v_cndmask_b32_e32 v95, v225, v95, vcc
	v_cmp_le_i32_e32 vcc, v2, v213
	v_or_b32_e32 v2, 33, v0
	s_nop 0
	v_cndmask_b32_e32 v96, v225, v96, vcc
	v_cmp_le_i32_e32 vcc, v2, v213
	v_or_b32_e32 v2, 34, v0
	s_nop 0
	v_cndmask_b32_e32 v97, v225, v97, vcc
	v_cmp_le_i32_e32 vcc, v2, v213
	v_or_b32_e32 v2, 35, v0
	s_nop 0
	v_cndmask_b32_e32 v98, v225, v98, vcc
	v_cmp_le_i32_e32 vcc, v2, v213
	v_or_b32_e32 v2, 36, v0
	s_nop 0
	v_cndmask_b32_e32 v99, v225, v99, vcc
	v_cmp_le_i32_e32 vcc, v2, v213
	v_or_b32_e32 v2, 37, v0
	s_nop 0
	v_cndmask_b32_e32 v100, v225, v100, vcc
	v_cmp_le_i32_e32 vcc, v2, v213
	v_or_b32_e32 v2, 38, v0
	s_nop 0
	v_cndmask_b32_e32 v101, v225, v101, vcc
	v_cmp_le_i32_e32 vcc, v2, v213
	v_or_b32_e32 v2, 39, v0
	s_nop 0
	v_cndmask_b32_e32 v102, v225, v102, vcc
	v_cmp_le_i32_e32 vcc, v2, v213
	v_or_b32_e32 v2, 48, v0
	s_nop 0
	v_cndmask_b32_e32 v103, v225, v103, vcc
	v_cmp_le_i32_e32 vcc, v2, v213
	v_or_b32_e32 v2, 49, v0
	s_nop 0
	v_cndmask_b32_e32 v104, v225, v104, vcc
	v_cmp_le_i32_e32 vcc, v2, v213
	v_or_b32_e32 v2, 50, v0
	s_nop 0
	v_cndmask_b32_e32 v105, v225, v105, vcc
	v_cmp_le_i32_e32 vcc, v2, v213
	v_or_b32_e32 v2, 51, v0
	s_nop 0
	v_cndmask_b32_e32 v106, v225, v106, vcc
	v_cmp_le_i32_e32 vcc, v2, v213
	v_or_b32_e32 v2, 52, v0
	s_nop 0
	v_cndmask_b32_e32 v107, v225, v107, vcc
	v_cmp_le_i32_e32 vcc, v2, v213
	v_or_b32_e32 v2, 53, v0
	s_nop 0
	v_cndmask_b32_e32 v108, v225, v108, vcc
	v_cmp_le_i32_e32 vcc, v2, v213
	v_or_b32_e32 v2, 54, v0
	v_or_b32_e32 v0, 55, v0
	v_cndmask_b32_e32 v109, v225, v109, vcc
	v_cmp_le_i32_e32 vcc, v2, v213
	s_nop 1
	v_cndmask_b32_e32 v110, v225, v110, vcc
	v_cmp_le_i32_e32 vcc, v0, v213
	s_nop 1
	v_cndmask_b32_e32 v111, v225, v111, vcc

; #define MFMA32(a, b, c) __builtin_amdgcn_mfma_f32_32x32x16_bf16((a), (b), (c), 0, 0, 0)
; DI f32x16 zero16() { f32x16 z; for (int i = 0; i < 16; ++i) z[i] = 0.f; return z; }
; template <int DQK, int MODE>
; DI void attn_core(const u16* __restrict__ Qg, int ldq, const u16* __restrict__ Kg, int ldk, const u16* __restrict__ Vtg,
;                   const u64* __restrict__ maskg, int q0, float scale, char* smem, int* sflags, f32x16 (&o)[4], float& l_run) {
;     ...
;   for (int it = 0; it < ntiles; ++it, tau += step) {
;     __syncthreads();
;     if (MODE == 2 && it > 0) {
;       if (!(sflags[0] | sflags[1] | sflags[2] | sflags[3] | sflags[4] | sflags[5] | sflags[6] | sflags[7])) break;
;     }
;     if (MODE == 2) gload(tau);
; #pragma unroll
;     for (int i = 0; i < NVK; ++i) {
;       const int v = tid + NT * i, row = v / VPR, c = v % VPR;
;       *(u32x4*)(Ks + row * KSTR + c * 8) = rk[i];
;     }
; #pragma unroll
;     for (int i = 0; i < 2; ++i) {
;       const int v = tid + NT * i, row = v >> 3, c = v & 7;
;       *(u32x4*)(Vs + row * 72 + c * 8) = rv[i];
;     }
;     __syncthreads();
;     if (MODE != 2 && it + 1 < ntiles) gload(tau + step);
;     if (tau * 64 > q0 + 32 * wid + 31) {
;       if (MODE == 2 && lane == 0) sflags[wid] = 1;
;       continue;
;     }
;     u64 mbits = 0;
;     if (MODE == 1) mbits = maskg[(long)qrow * 64 + tau] >> (8 * hh);
;     f32x16 s[2];
;     s[0] = zero16(); s[1] = zero16();
; #pragma unroll
;     for (int kt = 0; kt < 2; ++kt)
; #pragma unroll
;       for (int ks = 0; ks < NKS; ++ks) {
;         const bf16x8 kf = *(const bf16x8*)(Ks + (32 * kt + krow) * KSTR + ks * 16 + hh * 8);
;         s[kt] = MFMA32(kf, qf[ks], s[kt]);
;       }
;     const int kbase = tau * 64 + 8 * hh;
;     if (MODE == 0 || MODE == 1) {
;       const bool need_mask = (MODE == 1) || (tau * 64 + 63 > q0 + 32 * wid);
;       float mx = -1e30f;
;       if (need_mask) {
; #pragma unroll
;         for (int kt = 0; kt < 2; ++kt)
; #pragma unroll
;           for (int i = 0; i < 16; ++i) {
;             bool valid;
;             if (MODE == 1) valid = (mbits >> (32 * kt + 16 * (i >> 3) + (i & 7))) & 1ull;
;             else valid = (kbase + 32 * kt + 16 * (i >> 3) + (i & 7)) <= qrow;
;             s[kt][i] = valid ? s[kt][i] : -1e30f;
;           }
.LBB0_240:
	s_add_i32 s4, s15, 64
	v_add_u32_e32 v0, s15, v156
	v_mad_i64_i32 v[2:3], s[6:7], v0, s75, v[146:147]
	s_ashr_i32 s5, s4, 31
	s_lshl_b64 s[6:7], s[4:5], 1
	s_waitcnt lgkmcnt(0)
	s_nop 0
	s_waitcnt vmcnt(0)
	ds_write_b128 v157, v[128:131]
	ds_write_b128 v158, v[136:139] offset:9216
	ds_write_b128 v159, v[132:135] offset:9216
	s_waitcnt lgkmcnt(0)
	s_barrier
	global_load_dwordx4 v[128:131], v[2:3], off offset:1024
	v_lshl_add_u64 v[2:3], v[142:143], 0, s[6:7]
	v_lshl_add_u64 v[4:5], v[144:145], 0, s[6:7]
	global_load_dwordx4 v[136:139], v[2:3], off
	global_load_dwordx4 v[132:135], v[4:5], off
	v_cmp_le_i32_e32 vcc, s15, v155
	s_and_saveexec_b64 s[6:7], vcc
	s_cbranch_execz .LBB0_246
	v_add_u32_e32 v0, v149, v154
	ds_read_b128 v[10:13], v0
	ds_read_b128 v[162:165], v0 offset:32
	ds_read_b128 v[166:169], v0 offset:64
	ds_read_b128 v[170:173], v0 offset:96
	ds_read_b128 v[174:177], v0 offset:4608
	ds_read_b128 v[178:181], v0 offset:4640
	s_add_i32 s5, s15, 63
	v_cmp_gt_i32_e32 vcc, s5, v152
	s_waitcnt lgkmcnt(5)
	v_mfma_f32_32x32x16_bf16 v[96:111], v[10:13], v[124:127], 0
	ds_read_b128 v[10:13], v0 offset:4672
	s_waitcnt lgkmcnt(5)
	v_mfma_f32_32x32x16_bf16 v[96:111], v[162:165], v[120:123], v[96:111]
	ds_read_b128 v[162:165], v0 offset:4704
	s_waitcnt lgkmcnt(5)
	v_mfma_f32_32x32x16_bf16 v[96:111], v[166:169], v[116:119], v[96:111]
	s_waitcnt lgkmcnt(4)
	v_mfma_f32_32x32x16_bf16 v[96:111], v[170:173], v[112:115], v[96:111]
	s_waitcnt lgkmcnt(3)
	v_mfma_f32_32x32x16_bf16 v[80:95], v[174:177], v[124:127], 0
	s_waitcnt lgkmcnt(2)
	v_mfma_f32_32x32x16_bf16 v[80:95], v[178:181], v[120:123], v[80:95]
	s_waitcnt lgkmcnt(1)
	v_mfma_f32_32x32x16_bf16 v[80:95], v[10:13], v[116:119], v[80:95]
	s_waitcnt lgkmcnt(0)
	v_mfma_f32_32x32x16_bf16 v[80:95], v[162:165], v[112:115], v[80:95]
	s_and_saveexec_b64 s[8:9], vcc
	s_cbranch_execz .LBB0_243
	v_add_u32_e32 v0, s15, v153
	v_cmp_le_i32_e32 vcc, v0, v151
	v_add_u32_e32 v2, 2, v0
	s_nop 0
	v_cndmask_b32_e32 v96, v225, v96, vcc
	v_cmp_lt_i32_e32 vcc, v0, v151
	s_nop 1
	v_cndmask_b32_e32 v97, v225, v97, vcc
	v_cmp_le_i32_e32 vcc, v2, v151
	v_add_u32_e32 v2, 3, v0
	s_nop 0
	v_cndmask_b32_e32 v98, v225, v98, vcc
	v_cmp_le_i32_e32 vcc, v2, v151
	v_add_u32_e32 v2, 4, v0
	s_nop 0
	v_cndmask_b32_e32 v99, v225, v99, vcc
	v_cmp_le_i32_e32 vcc, v2, v151
	v_add_u32_e32 v2, 5, v0
	s_nop 0
	v_cndmask_b32_e32 v100, v225, v100, vcc
	v_cmp_le_i32_e32 vcc, v2, v151
	v_add_u32_e32 v2, 6, v0
	s_nop 0
	v_cndmask_b32_e32 v101, v225, v101, vcc
	v_cmp_le_i32_e32 vcc, v2, v151
	v_add_u32_e32 v2, 7, v0
	s_nop 0
	v_cndmask_b32_e32 v102, v225, v102, vcc
	v_cmp_le_i32_e32 vcc, v2, v151
	v_add_u32_e32 v2, 16, v0
	s_nop 0
	v_cndmask_b32_e32 v103, v225, v103, vcc
	v_cmp_le_i32_e32 vcc, v2, v151
	v_add_u32_e32 v2, 17, v0
	s_nop 0
	v_cndmask_b32_e32 v104, v225, v104, vcc
	v_cmp_le_i32_e32 vcc, v2, v151
	v_add_u32_e32 v2, 18, v0
	s_nop 0
	v_cndmask_b32_e32 v105, v225, v105, vcc
	v_cmp_le_i32_e32 vcc, v2, v151
	v_add_u32_e32 v2, 19, v0
	s_nop 0
	v_cndmask_b32_e32 v106, v225, v106, vcc
	v_cmp_le_i32_e32 vcc, v2, v151
	v_add_u32_e32 v2, 20, v0
	s_nop 0
	v_cndmask_b32_e32 v107, v225, v107, vcc
	v_cmp_le_i32_e32 vcc, v2, v151
	v_add_u32_e32 v2, 21, v0
	s_nop 0
	v_cndmask_b32_e32 v108, v225, v108, vcc
	v_cmp_le_i32_e32 vcc, v2, v151
	v_add_u32_e32 v2, 22, v0
	s_nop 0
	v_cndmask_b32_e32 v109, v225, v109, vcc
	v_cmp_le_i32_e32 vcc, v2, v151
	v_add_u32_e32 v2, 23, v0
	s_nop 0
	v_cndmask_b32_e32 v110, v225, v110, vcc
	v_cmp_le_i32_e32 vcc, v2, v151
	v_add_u32_e32 v2, 32, v0
	s_nop 0
	v_cndmask_b32_e32 v111, v225, v111, vcc
	v_cmp_le_i32_e32 vcc, v2, v151
	v_add_u32_e32 v2, 33, v0
	s_nop 0
	v_cndmask_b32_e32 v80, v225, v80, vcc
	v_cmp_le_i32_e32 vcc, v2, v151
	v_add_u32_e32 v2, 34, v0
	s_nop 0
	v_cndmask_b32_e32 v81, v225, v81, vcc
	v_cmp_le_i32_e32 vcc, v2, v151
	v_add_u32_e32 v2, 35, v0
	s_nop 0
	v_cndmask_b32_e32 v82, v225, v82, vcc
	v_cmp_le_i32_e32 vcc, v2, v151
	v_add_u32_e32 v2, 36, v0
	s_nop 0
	v_cndmask_b32_e32 v83, v225, v83, vcc
	v_cmp_le_i32_e32 vcc, v2, v151
	v_add_u32_e32 v2, 37, v0
	s_nop 0
	v_cndmask_b32_e32 v84, v225, v84, vcc
	v_cmp_le_i32_e32 vcc, v2, v151
	v_add_u32_e32 v2, 38, v0
	s_nop 0
	v_cndmask_b32_e32 v85, v225, v85, vcc
	v_cmp_le_i32_e32 vcc, v2, v151
	v_add_u32_e32 v2, 39, v0
	s_nop 0
	v_cndmask_b32_e32 v86, v225, v86, vcc
	v_cmp_le_i32_e32 vcc, v2, v151
	v_add_u32_e32 v2, 48, v0
	s_nop 0
	v_cndmask_b32_e32 v87, v225, v87, vcc
	v_cmp_le_i32_e32 vcc, v2, v151
	v_add_u32_e32 v2, 49, v0
	s_nop 0
	v_cndmask_b32_e32 v88, v225, v88, vcc
	v_cmp_le_i32_e32 vcc, v2, v151
	v_add_u32_e32 v2, 50, v0
	s_nop 0
	v_cndmask_b32_e32 v89, v225, v89, vcc
	v_cmp_le_i32_e32 vcc, v2, v151
	v_add_u32_e32 v2, 51, v0
	s_nop 0
	v_cndmask_b32_e32 v90, v225, v90, vcc
	v_cmp_le_i32_e32 vcc, v2, v151
	v_add_u32_e32 v2, 52, v0
	s_nop 0
	v_cndmask_b32_e32 v91, v225, v91, vcc
	v_cmp_le_i32_e32 vcc, v2, v151
	v_add_u32_e32 v2, 53, v0
	s_nop 0
	v_cndmask_b32_e32 v92, v225, v92, vcc
	v_cmp_le_i32_e32 vcc, v2, v151
	v_add_u32_e32 v2, 54, v0
	v_add_u32_e32 v0, 55, v0
	v_cndmask_b32_e32 v93, v225, v93, vcc
	v_cmp_le_i32_e32 vcc, v2, v151
	s_nop 1
	v_cndmask_b32_e32 v94, v225, v94, vcc
	v_cmp_le_i32_e32 vcc, v0, v151
	s_nop 1
	v_cndmask_b32_e32 v95, v225, v95, vcc

; #define MFMA32(a, b, c) __builtin_amdgcn_mfma_f32_32x32x16_bf16((a), (b), (c), 0, 0, 0)
; DI f32x16 zero16() { f32x16 z; for (int i = 0; i < 16; ++i) z[i] = 0.f; return z; }
; template <int DQK, int MODE>
; DI void attn_core(const u16* __restrict__ Qg, int ldq, const u16* __restrict__ Kg, int ldk, const u16* __restrict__ Vtg,
;                   const u64* __restrict__ maskg, int q0, float scale, char* smem, int* sflags, f32x16 (&o)[4], float& l_run) {
;     ...
;   for (int it = 0; it < ntiles; ++it, tau += step) {
;     __syncthreads();
;     if (MODE == 2 && it > 0) {
;       if (!(sflags[0] | sflags[1] | sflags[2] | sflags[3] | sflags[4] | sflags[5] | sflags[6] | sflags[7])) break;
;     }
;     if (MODE == 2) gload(tau);
; #pragma unroll
;     for (int i = 0; i < NVK; ++i) {
;       const int v = tid + NT * i, row = v / VPR, c = v % VPR;
;       *(u32x4*)(Ks + row * KSTR + c * 8) = rk[i];
;     }
; #pragma unroll
;     for (int i = 0; i < 2; ++i) {
;       const int v = tid + NT * i, row = v >> 3, c = v & 7;
;       *(u32x4*)(Vs + row * 72 + c * 8) = rv[i];
;     }
;     __syncthreads();
;     if (MODE != 2 && it + 1 < ntiles) gload(tau + step);
;     if (tau * 64 > q0 + 32 * wid + 31) {
;       if (MODE == 2 && lane == 0) sflags[wid] = 1;
;       continue;
;     }
;     u64 mbits = 0;
;     if (MODE == 1) mbits = maskg[(long)qrow * 64 + tau] >> (8 * hh);
;     f32x16 s[2];
;     s[0] = zero16(); s[1] = zero16();
; #pragma unroll
;     for (int kt = 0; kt < 2; ++kt)
; #pragma unroll
;       for (int ks = 0; ks < NKS; ++ks) {
;         const bf16x8 kf = *(const bf16x8*)(Ks + (32 * kt + krow) * KSTR + ks * 16 + hh * 8);
;         s[kt] = MFMA32(kf, qf[ks], s[kt]);
;       }
;     const int kbase = tau * 64 + 8 * hh;
;     if (MODE == 0 || MODE == 1) {
;       const bool need_mask = (MODE == 1) || (tau * 64 + 63 > q0 + 32 * wid);
;       float mx = -1e30f;
;       if (need_mask) {
; #pragma unroll
;         for (int kt = 0; kt < 2; ++kt)
; #pragma unroll
;           for (int i = 0; i < 16; ++i) {
;             bool valid;
;             if (MODE == 1) valid = (mbits >> (32 * kt + 16 * (i >> 3) + (i & 7))) & 1ull;
;             else valid = (kbase + 32 * kt + 16 * (i >> 3) + (i & 7)) <= qrow;
;             s[kt][i] = valid ? s[kt][i] : -1e30f;
;           }
.LBB0_246:
	s_or_b64 exec, exec, s[6:7]
	v_xor_b32_e32 v157, 0x10000, v157
	v_xor_b32_e32 v158, 0x10000, v158
	v_xor_b32_e32 v159, 0x10000, v159
	v_xor_b32_e32 v149, 0x10000, v149
	s_add_i32 s14, s14, 1
	s_cmp_eq_u32 s13, s14
	s_cbranch_scc1 .LBB0_248
	s_mov_b32 s15, s4
	s_branch .LBB0_240
.LBB0_248:
	s_lshl_b32 s8, s13, 6
	v_cmp_le_i32_e32 vcc, s8, v155
	s_nop 0
	s_waitcnt vmcnt(2)
	ds_write_b128 v157, v[128:131]
	s_waitcnt vmcnt(1)
	ds_write_b128 v158, v[136:139] offset:9216
	s_waitcnt vmcnt(0)
	ds_write_b128 v159, v[132:135] offset:9216
	s_waitcnt lgkmcnt(0)
	s_barrier
	s_and_saveexec_b64 s[4:5], vcc
	s_xor_b64 s[4:5], exec, s[4:5]
	s_cbranch_execz .LBB0_255
	v_add_u32_e32 v0, v149, v154
	ds_read_b128 v[10:13], v0
	ds_read_b128 v[128:131], v0 offset:32
	ds_read_b128 v[132:135], v0 offset:64
	ds_read_b128 v[136:139], v0 offset:96
	ds_read_b128 v[142:145], v0 offset:4608
	ds_read_b128 v[154:157], v0 offset:4640
	s_or_b32 s6, s8, 63
	v_cmp_gt_i32_e32 vcc, s6, v152
	s_waitcnt lgkmcnt(5)
	v_mfma_f32_32x32x16_bf16 v[96:111], v[10:13], v[124:127], 0
	ds_read_b128 v[10:13], v0 offset:4672
	s_waitcnt lgkmcnt(5)
	v_mfma_f32_32x32x16_bf16 v[96:111], v[128:131], v[120:123], v[96:111]
	ds_read_b128 v[128:131], v0 offset:4704
	s_waitcnt lgkmcnt(5)
	v_mfma_f32_32x32x16_bf16 v[96:111], v[132:135], v[116:119], v[96:111]
	s_waitcnt lgkmcnt(4)
	v_mfma_f32_32x32x16_bf16 v[96:111], v[136:139], v[112:115], v[96:111]
	s_waitcnt lgkmcnt(3)
	v_mfma_f32_32x32x16_bf16 v[80:95], v[142:145], v[124:127], 0
	s_waitcnt lgkmcnt(2)
	v_mfma_f32_32x32x16_bf16 v[80:95], v[154:157], v[120:123], v[80:95]
	s_waitcnt lgkmcnt(1)
	v_mfma_f32_32x32x16_bf16 v[80:95], v[10:13], v[116:119], v[80:95]
	s_waitcnt lgkmcnt(0)
	v_mfma_f32_32x32x16_bf16 v[80:95], v[128:131], v[112:115], v[80:95]
	s_and_saveexec_b64 s[6:7], vcc
	s_cbranch_execz .LBB0_251
	v_or_b32_e32 v0, s8, v153
	v_cmp_le_i32_e32 vcc, v0, v151
	v_or_b32_e32 v2, 2, v0
	s_nop 0
	v_cndmask_b32_e32 v96, v225, v96, vcc
	v_cmp_lt_i32_e32 vcc, v0, v151
	s_nop 1
	v_cndmask_b32_e32 v97, v225, v97, vcc
	v_cmp_le_i32_e32 vcc, v2, v151
	v_or_b32_e32 v2, 3, v0
	s_nop 0
	v_cndmask_b32_e32 v98, v225, v98, vcc
	v_cmp_le_i32_e32 vcc, v2, v151
	v_or_b32_e32 v2, 4, v0
	s_nop 0
	v_cndmask_b32_e32 v99, v225, v99, vcc
	v_cmp_le_i32_e32 vcc, v2, v151
	v_or_b32_e32 v2, 5, v0
	s_nop 0
	v_cndmask_b32_e32 v100, v225, v100, vcc
	v_cmp_le_i32_e32 vcc, v2, v151
	v_or_b32_e32 v2, 6, v0
	s_nop 0
	v_cndmask_b32_e32 v101, v225, v101, vcc
	v_cmp_le_i32_e32 vcc, v2, v151
	v_or_b32_e32 v2, 7, v0
	s_nop 0
	v_cndmask_b32_e32 v102, v225, v102, vcc
	v_cmp_le_i32_e32 vcc, v2, v151
	v_or_b32_e32 v2, 16, v0
	s_nop 0
	v_cndmask_b32_e32 v103, v225, v103, vcc
	v_cmp_le_i32_e32 vcc, v2, v151
	v_or_b32_e32 v2, 17, v0
	s_nop 0
	v_cndmask_b32_e32 v104, v225, v104, vcc
	v_cmp_le_i32_e32 vcc, v2, v151
	v_or_b32_e32 v2, 18, v0
	s_nop 0
	v_cndmask_b32_e32 v105, v225, v105, vcc
	v_cmp_le_i32_e32 vcc, v2, v151
	v_or_b32_e32 v2, 19, v0
	s_nop 0
	v_cndmask_b32_e32 v106, v225, v106, vcc
	v_cmp_le_i32_e32 vcc, v2, v151
	v_or_b32_e32 v2, 20, v0
	s_nop 0
	v_cndmask_b32_e32 v107, v225, v107, vcc
	v_cmp_le_i32_e32 vcc, v2, v151
	v_or_b32_e32 v2, 21, v0
	s_nop 0
	v_cndmask_b32_e32 v108, v225, v108, vcc
	v_cmp_le_i32_e32 vcc, v2, v151
	v_or_b32_e32 v2, 22, v0
	s_nop 0
	v_cndmask_b32_e32 v109, v225, v109, vcc
	v_cmp_le_i32_e32 vcc, v2, v151
	v_or_b32_e32 v2, 23, v0
	s_nop 0
	v_cndmask_b32_e32 v110, v225, v110, vcc
	v_cmp_le_i32_e32 vcc, v2, v151
	v_or_b32_e32 v2, 32, v0
	s_nop 0
	v_cndmask_b32_e32 v111, v225, v111, vcc
	v_cmp_le_i32_e32 vcc, v2, v151
	v_or_b32_e32 v2, 33, v0
	s_nop 0
	v_cndmask_b32_e32 v80, v225, v80, vcc
	v_cmp_le_i32_e32 vcc, v2, v151
	v_or_b32_e32 v2, 34, v0
	s_nop 0
	v_cndmask_b32_e32 v81, v225, v81, vcc
	v_cmp_le_i32_e32 vcc, v2, v151
	v_or_b32_e32 v2, 35, v0
	s_nop 0
	v_cndmask_b32_e32 v82, v225, v82, vcc
	v_cmp_le_i32_e32 vcc, v2, v151
	v_or_b32_e32 v2, 36, v0
	s_nop 0
	v_cndmask_b32_e32 v83, v225, v83, vcc
	v_cmp_le_i32_e32 vcc, v2, v151
	v_or_b32_e32 v2, 37, v0
	s_nop 0
	v_cndmask_b32_e32 v84, v225, v84, vcc
	v_cmp_le_i32_e32 vcc, v2, v151
	v_or_b32_e32 v2, 38, v0
	s_nop 0
	v_cndmask_b32_e32 v85, v225, v85, vcc
	v_cmp_le_i32_e32 vcc, v2, v151
	v_or_b32_e32 v2, 39, v0
	s_nop 0
	v_cndmask_b32_e32 v86, v225, v86, vcc
	v_cmp_le_i32_e32 vcc, v2, v151
	v_or_b32_e32 v2, 48, v0
	s_nop 0
	v_cndmask_b32_e32 v87, v225, v87, vcc
	v_cmp_le_i32_e32 vcc, v2, v151
	v_or_b32_e32 v2, 49, v0
	s_nop 0
	v_cndmask_b32_e32 v88, v225, v88, vcc
	v_cmp_le_i32_e32 vcc, v2, v151
	v_or_b32_e32 v2, 50, v0
	s_nop 0
	v_cndmask_b32_e32 v89, v225, v89, vcc
	v_cmp_le_i32_e32 vcc, v2, v151
	v_or_b32_e32 v2, 51, v0
	s_nop 0
	v_cndmask_b32_e32 v90, v225, v90, vcc
	v_cmp_le_i32_e32 vcc, v2, v151
	v_or_b32_e32 v2, 52, v0
	s_nop 0
	v_cndmask_b32_e32 v91, v225, v91, vcc
	v_cmp_le_i32_e32 vcc, v2, v151
	v_or_b32_e32 v2, 53, v0
	s_nop 0
	v_cndmask_b32_e32 v92, v225, v92, vcc
	v_cmp_le_i32_e32 vcc, v2, v151
	v_or_b32_e32 v2, 54, v0
	v_or_b32_e32 v0, 55, v0
	v_cndmask_b32_e32 v93, v225, v93, vcc
	v_cmp_le_i32_e32 vcc, v2, v151
	s_nop 1
	v_cndmask_b32_e32 v94, v225, v94, vcc
	v_cmp_le_i32_e32 vcc, v0, v151
	s_nop 1
	v_cndmask_b32_e32 v95, v225, v95, vcc

; #define MFMA32(a, b, c) __builtin_amdgcn_mfma_f32_32x32x16_bf16((a), (b), (c), 0, 0, 0)
; DI f32x16 zero16() { f32x16 z; for (int i = 0; i < 16; ++i) z[i] = 0.f; return z; }
; template <int DQK, int MODE>
; DI void attn_core(const u16* __restrict__ Qg, int ldq, const u16* __restrict__ Kg, int ldk, const u16* __restrict__ Vtg,
;                   const u64* __restrict__ maskg, int q0, float scale, char* smem, int* sflags, f32x16 (&o)[4], float& l_run) {
;     ...
;   for (int it = 0; it < ntiles; ++it, tau += step) {
;     __syncthreads();
;     if (MODE == 2 && it > 0) {
;       if (!(sflags[0] | sflags[1] | sflags[2] | sflags[3] | sflags[4] | sflags[5] | sflags[6] | sflags[7])) break;
;     }
;     if (MODE == 2) gload(tau);
; #pragma unroll
;     for (int i = 0; i < NVK; ++i) {
;       const int v = tid + NT * i, row = v / VPR, c = v % VPR;
;       *(u32x4*)(Ks + row * KSTR + c * 8) = rk[i];
;     }
; #pragma unroll
;     for (int i = 0; i < 2; ++i) {
;       const int v = tid + NT * i, row = v >> 3, c = v & 7;
;       *(u32x4*)(Vs + row * 72 + c * 8) = rv[i];
;     }
;     __syncthreads();
;     if (MODE != 2 && it + 1 < ntiles) gload(tau + step);
;     if (tau * 64 > q0 + 32 * wid + 31) {
;       if (MODE == 2 && lane == 0) sflags[wid] = 1;
;       continue;
;     }
;     u64 mbits = 0;
;     if (MODE == 1) mbits = maskg[(long)qrow * 64 + tau] >> (8 * hh);
;     f32x16 s[2];
;     s[0] = zero16(); s[1] = zero16();
; #pragma unroll
;     for (int kt = 0; kt < 2; ++kt)
; #pragma unroll
;       for (int ks = 0; ks < NKS; ++ks) {
;         const bf16x8 kf = *(const bf16x8*)(Ks + (32 * kt + krow) * KSTR + ks * 16 + hh * 8);
;         s[kt] = MFMA32(kf, qf[ks], s[kt]);
;       }
;     const int kbase = tau * 64 + 8 * hh;
;     if (MODE == 0 || MODE == 1) {
;       const bool need_mask = (MODE == 1) || (tau * 64 + 63 > q0 + 32 * wid);
;       float mx = -1e30f;
;       if (need_mask) {
; #pragma unroll
;         for (int kt = 0; kt < 2; ++kt)
; #pragma unroll
;           for (int i = 0; i < 16; ++i) {
;             bool valid;
;             if (MODE == 1) valid = (mbits >> (32 * kt + 16 * (i >> 3) + (i & 7))) & 1ull;
;             else valid = (kbase + 32 * kt + 16 * (i >> 3) + (i & 7)) <= qrow;
;             s[kt][i] = valid ? s[kt][i] : -1e30f;
;           }
.LBB0_258:
	s_add_i32 s0, s7, 64
	v_add_u32_e32 v0, s7, v158
	v_mad_i64_i32 v[2:3], s[2:3], v0, s75, v[150:151]
	s_ashr_i32 s1, s0, 31
	s_lshl_b64 s[2:3], s[0:1], 1
	s_nop 0
	s_waitcnt vmcnt(0)
	ds_write_b128 v159, v[128:131]
	ds_write_b128 v160, v[136:139] offset:9216
	ds_write_b128 v161, v[132:135] offset:9216
	s_waitcnt lgkmcnt(0)
	s_barrier
	global_load_dwordx4 v[128:131], v[2:3], off offset:1152
	v_lshl_add_u64 v[2:3], v[146:147], 0, s[2:3]
	v_lshl_add_u64 v[4:5], v[148:149], 0, s[2:3]
	global_load_dwordx4 v[136:139], v[2:3], off
	global_load_dwordx4 v[132:135], v[4:5], off
	v_cmp_le_i32_e32 vcc, s7, v157
	s_and_saveexec_b64 s[2:3], vcc
	s_cbranch_execz .LBB0_264
	v_add_u32_e32 v0, v142, v156
	ds_read_b128 v[10:13], v0
	ds_read_b128 v[164:167], v0 offset:32
	ds_read_b128 v[168:171], v0 offset:64
	ds_read_b128 v[172:175], v0 offset:96
	ds_read_b128 v[176:179], v0 offset:4608
	ds_read_b128 v[180:183], v0 offset:4640
	s_add_i32 s1, s7, 63
	v_cmp_gt_i32_e32 vcc, s1, v154
	s_waitcnt lgkmcnt(5)
	v_mfma_f32_32x32x16_bf16 v[96:111], v[10:13], v[124:127], 0
	ds_read_b128 v[10:13], v0 offset:4672
	s_waitcnt lgkmcnt(5)
	v_mfma_f32_32x32x16_bf16 v[96:111], v[164:167], v[120:123], v[96:111]
	ds_read_b128 v[164:167], v0 offset:4704
	s_waitcnt lgkmcnt(5)
	v_mfma_f32_32x32x16_bf16 v[96:111], v[168:171], v[116:119], v[96:111]
	s_waitcnt lgkmcnt(4)
	v_mfma_f32_32x32x16_bf16 v[96:111], v[172:175], v[112:115], v[96:111]
	s_waitcnt lgkmcnt(3)
	v_mfma_f32_32x32x16_bf16 v[80:95], v[176:179], v[124:127], 0
	s_waitcnt lgkmcnt(2)
	v_mfma_f32_32x32x16_bf16 v[80:95], v[180:183], v[120:123], v[80:95]
	s_waitcnt lgkmcnt(1)
	v_mfma_f32_32x32x16_bf16 v[80:95], v[10:13], v[116:119], v[80:95]
	s_waitcnt lgkmcnt(0)
	v_mfma_f32_32x32x16_bf16 v[80:95], v[164:167], v[112:115], v[80:95]
	s_and_saveexec_b64 s[4:5], vcc
	s_cbranch_execz .LBB0_261
	v_add_u32_e32 v0, s7, v155
	v_cmp_le_i32_e32 vcc, v0, v153
	v_add_u32_e32 v2, 2, v0
	s_nop 0
	v_cndmask_b32_e32 v96, v225, v96, vcc
	v_cmp_lt_i32_e32 vcc, v0, v153
	s_nop 1
	v_cndmask_b32_e32 v97, v225, v97, vcc
	v_cmp_le_i32_e32 vcc, v2, v153
	v_add_u32_e32 v2, 3, v0
	s_nop 0
	v_cndmask_b32_e32 v98, v225, v98, vcc
	v_cmp_le_i32_e32 vcc, v2, v153
	v_add_u32_e32 v2, 4, v0
	s_nop 0
	v_cndmask_b32_e32 v99, v225, v99, vcc
	v_cmp_le_i32_e32 vcc, v2, v153
	v_add_u32_e32 v2, 5, v0
	s_nop 0
	v_cndmask_b32_e32 v100, v225, v100, vcc
	v_cmp_le_i32_e32 vcc, v2, v153
	v_add_u32_e32 v2, 6, v0
	s_nop 0
	v_cndmask_b32_e32 v101, v225, v101, vcc
	v_cmp_le_i32_e32 vcc, v2, v153
	v_add_u32_e32 v2, 7, v0
	s_nop 0
	v_cndmask_b32_e32 v102, v225, v102, vcc
	v_cmp_le_i32_e32 vcc, v2, v153
	v_add_u32_e32 v2, 16, v0
	s_nop 0
	v_cndmask_b32_e32 v103, v225, v103, vcc
	v_cmp_le_i32_e32 vcc, v2, v153
	v_add_u32_e32 v2, 17, v0
	s_nop 0
	v_cndmask_b32_e32 v104, v225, v104, vcc
	v_cmp_le_i32_e32 vcc, v2, v153
	v_add_u32_e32 v2, 18, v0
	s_nop 0
	v_cndmask_b32_e32 v105, v225, v105, vcc
	v_cmp_le_i32_e32 vcc, v2, v153
	v_add_u32_e32 v2, 19, v0
	s_nop 0
	v_cndmask_b32_e32 v106, v225, v106, vcc
	v_cmp_le_i32_e32 vcc, v2, v153
	v_add_u32_e32 v2, 20, v0
	s_nop 0
	v_cndmask_b32_e32 v107, v225, v107, vcc
	v_cmp_le_i32_e32 vcc, v2, v153
	v_add_u32_e32 v2, 21, v0
	s_nop 0
	v_cndmask_b32_e32 v108, v225, v108, vcc
	v_cmp_le_i32_e32 vcc, v2, v153
	v_add_u32_e32 v2, 22, v0
	s_nop 0
	v_cndmask_b32_e32 v109, v225, v109, vcc
	v_cmp_le_i32_e32 vcc, v2, v153
	v_add_u32_e32 v2, 23, v0
	s_nop 0
	v_cndmask_b32_e32 v110, v225, v110, vcc
	v_cmp_le_i32_e32 vcc, v2, v153
	v_add_u32_e32 v2, 32, v0
	s_nop 0
	v_cndmask_b32_e32 v111, v225, v111, vcc
	v_cmp_le_i32_e32 vcc, v2, v153
	v_add_u32_e32 v2, 33, v0
	s_nop 0
	v_cndmask_b32_e32 v80, v225, v80, vcc
	v_cmp_le_i32_e32 vcc, v2, v153
	v_add_u32_e32 v2, 34, v0
	s_nop 0
	v_cndmask_b32_e32 v81, v225, v81, vcc
	v_cmp_le_i32_e32 vcc, v2, v153
	v_add_u32_e32 v2, 35, v0
	s_nop 0
	v_cndmask_b32_e32 v82, v225, v82, vcc
	v_cmp_le_i32_e32 vcc, v2, v153
	v_add_u32_e32 v2, 36, v0
	s_nop 0
	v_cndmask_b32_e32 v83, v225, v83, vcc
	v_cmp_le_i32_e32 vcc, v2, v153
	v_add_u32_e32 v2, 37, v0
	s_nop 0
	v_cndmask_b32_e32 v84, v225, v84, vcc
	v_cmp_le_i32_e32 vcc, v2, v153
	v_add_u32_e32 v2, 38, v0
	s_nop 0
	v_cndmask_b32_e32 v85, v225, v85, vcc
	v_cmp_le_i32_e32 vcc, v2, v153
	v_add_u32_e32 v2, 39, v0
	s_nop 0
	v_cndmask_b32_e32 v86, v225, v86, vcc
	v_cmp_le_i32_e32 vcc, v2, v153
	v_add_u32_e32 v2, 48, v0
	s_nop 0
	v_cndmask_b32_e32 v87, v225, v87, vcc
	v_cmp_le_i32_e32 vcc, v2, v153
	v_add_u32_e32 v2, 49, v0
	s_nop 0
	v_cndmask_b32_e32 v88, v225, v88, vcc
	v_cmp_le_i32_e32 vcc, v2, v153
	v_add_u32_e32 v2, 50, v0
	s_nop 0
	v_cndmask_b32_e32 v89, v225, v89, vcc
	v_cmp_le_i32_e32 vcc, v2, v153
	v_add_u32_e32 v2, 51, v0
	s_nop 0
	v_cndmask_b32_e32 v90, v225, v90, vcc
	v_cmp_le_i32_e32 vcc, v2, v153
	v_add_u32_e32 v2, 52, v0
	s_nop 0
	v_cndmask_b32_e32 v91, v225, v91, vcc
	v_cmp_le_i32_e32 vcc, v2, v153
	v_add_u32_e32 v2, 53, v0
	s_nop 0
	v_cndmask_b32_e32 v92, v225, v92, vcc
	v_cmp_le_i32_e32 vcc, v2, v153
	v_add_u32_e32 v2, 54, v0
	v_add_u32_e32 v0, 55, v0
	v_cndmask_b32_e32 v93, v225, v93, vcc
	v_cmp_le_i32_e32 vcc, v2, v153
	s_nop 1
	v_cndmask_b32_e32 v94, v225, v94, vcc
	v_cmp_le_i32_e32 vcc, v0, v153
	s_nop 1
	v_cndmask_b32_e32 v95, v225, v95, vcc

; #define MFMA32(a, b, c) __builtin_amdgcn_mfma_f32_32x32x16_bf16((a), (b), (c), 0, 0, 0)
; DI f32x16 zero16() { f32x16 z; for (int i = 0; i < 16; ++i) z[i] = 0.f; return z; }
; template <int DQK, int MODE>
; DI void attn_core(const u16* __restrict__ Qg, int ldq, const u16* __restrict__ Kg, int ldk, const u16* __restrict__ Vtg,
;                   const u64* __restrict__ maskg, int q0, float scale, char* smem, int* sflags, f32x16 (&o)[4], float& l_run) {
;     ...
;   for (int it = 0; it < ntiles; ++it, tau += step) {
;     __syncthreads();
;     if (MODE == 2 && it > 0) {
;       if (!(sflags[0] | sflags[1] | sflags[2] | sflags[3] | sflags[4] | sflags[5] | sflags[6] | sflags[7])) break;
;     }
;     if (MODE == 2) gload(tau);
; #pragma unroll
;     for (int i = 0; i < NVK; ++i) {
;       const int v = tid + NT * i, row = v / VPR, c = v % VPR;
;       *(u32x4*)(Ks + row * KSTR + c * 8) = rk[i];
;     }
; #pragma unroll
;     for (int i = 0; i < 2; ++i) {
;       const int v = tid + NT * i, row = v >> 3, c = v & 7;
;       *(u32x4*)(Vs + row * 72 + c * 8) = rv[i];
;     }
;     __syncthreads();
;     if (MODE != 2 && it + 1 < ntiles) gload(tau + step);
;     if (tau * 64 > q0 + 32 * wid + 31) {
;       if (MODE == 2 && lane == 0) sflags[wid] = 1;
;       continue;
;     }
;     u64 mbits = 0;
;     if (MODE == 1) mbits = maskg[(long)qrow * 64 + tau] >> (8 * hh);
;     f32x16 s[2];
;     s[0] = zero16(); s[1] = zero16();
; #pragma unroll
;     for (int kt = 0; kt < 2; ++kt)
; #pragma unroll
;       for (int ks = 0; ks < NKS; ++ks) {
;         const bf16x8 kf = *(const bf16x8*)(Ks + (32 * kt + krow) * KSTR + ks * 16 + hh * 8);
;         s[kt] = MFMA32(kf, qf[ks], s[kt]);
;       }
;     const int kbase = tau * 64 + 8 * hh;
;     if (MODE == 0 || MODE == 1) {
;       const bool need_mask = (MODE == 1) || (tau * 64 + 63 > q0 + 32 * wid);
;       float mx = -1e30f;
;       if (need_mask) {
; #pragma unroll
;         for (int kt = 0; kt < 2; ++kt)
; #pragma unroll
;           for (int i = 0; i < 16; ++i) {
;             bool valid;
;             if (MODE == 1) valid = (mbits >> (32 * kt + 16 * (i >> 3) + (i & 7))) & 1ull;
;             else valid = (kbase + 32 * kt + 16 * (i >> 3) + (i & 7)) <= qrow;
;             s[kt][i] = valid ? s[kt][i] : -1e30f;
;           }
.LBB0_264:
	s_or_b64 exec, exec, s[2:3]
	v_xor_b32_e32 v159, 0x10000, v159
	v_xor_b32_e32 v160, 0x10000, v160
	v_xor_b32_e32 v161, 0x10000, v161
	v_xor_b32_e32 v142, 0x10000, v142
	s_add_i32 s6, s6, 1
	s_cmp_eq_u32 s13, s6
	s_cbranch_scc1 .LBB0_266
	s_mov_b32 s7, s0
	s_branch .LBB0_258
.LBB0_266:
	v_cmp_le_i32_e32 vcc, s8, v157
	s_nop 0
	s_waitcnt vmcnt(2)
	ds_write_b128 v159, v[128:131]
	s_waitcnt vmcnt(1)
	ds_write_b128 v160, v[136:139] offset:9216
	s_waitcnt vmcnt(0)
	ds_write_b128 v161, v[132:135] offset:9216
	s_waitcnt lgkmcnt(0)
	s_barrier
	s_and_saveexec_b64 s[0:1], vcc
	s_cbranch_execz .LBB0_201
	v_add_u32_e32 v0, v142, v156
	ds_read_b128 v[10:13], v0
	ds_read_b128 v[128:131], v0 offset:32
	ds_read_b128 v[132:135], v0 offset:64
	ds_read_b128 v[136:139], v0 offset:96
	ds_read_b128 v[146:149], v0 offset:4608
	ds_read_b128 v[156:159], v0 offset:4640
	s_or_b32 s2, s8, 63
	v_cmp_gt_i32_e32 vcc, s2, v154
	s_waitcnt lgkmcnt(5)
	v_mfma_f32_32x32x16_bf16 v[96:111], v[10:13], v[124:127], 0
	ds_read_b128 v[10:13], v0 offset:4672
	s_waitcnt lgkmcnt(5)
	v_mfma_f32_32x32x16_bf16 v[96:111], v[128:131], v[120:123], v[96:111]
	ds_read_b128 v[128:131], v0 offset:4704
	s_waitcnt lgkmcnt(5)
	v_mfma_f32_32x32x16_bf16 v[96:111], v[132:135], v[116:119], v[96:111]
	s_waitcnt lgkmcnt(4)
	v_mfma_f32_32x32x16_bf16 v[96:111], v[136:139], v[112:115], v[96:111]
	s_waitcnt lgkmcnt(3)
	v_mfma_f32_32x32x16_bf16 v[80:95], v[146:149], v[124:127], 0
	s_waitcnt lgkmcnt(2)
	v_mfma_f32_32x32x16_bf16 v[80:95], v[156:159], v[120:123], v[80:95]
	s_waitcnt lgkmcnt(1)
	v_mfma_f32_32x32x16_bf16 v[80:95], v[10:13], v[116:119], v[80:95]
	s_waitcnt lgkmcnt(0)
	v_mfma_f32_32x32x16_bf16 v[80:95], v[128:131], v[112:115], v[80:95]
	s_and_saveexec_b64 s[2:3], vcc
	s_cbranch_execz .LBB0_269
	v_or_b32_e32 v0, s8, v155
	v_cmp_le_i32_e32 vcc, v0, v153
	v_or_b32_e32 v2, 2, v0
	s_nop 0
	v_cndmask_b32_e32 v96, v225, v96, vcc
	v_cmp_lt_i32_e32 vcc, v0, v153
	s_nop 1
	v_cndmask_b32_e32 v97, v225, v97, vcc
	v_cmp_le_i32_e32 vcc, v2, v153
	v_or_b32_e32 v2, 3, v0
	s_nop 0
	v_cndmask_b32_e32 v98, v225, v98, vcc
	v_cmp_le_i32_e32 vcc, v2, v153
	v_or_b32_e32 v2, 4, v0
	s_nop 0
	v_cndmask_b32_e32 v99, v225, v99, vcc
	v_cmp_le_i32_e32 vcc, v2, v153
	v_or_b32_e32 v2, 5, v0
	s_nop 0
	v_cndmask_b32_e32 v100, v225, v100, vcc
	v_cmp_le_i32_e32 vcc, v2, v153
	v_or_b32_e32 v2, 6, v0
	s_nop 0
	v_cndmask_b32_e32 v101, v225, v101, vcc
	v_cmp_le_i32_e32 vcc, v2, v153
	v_or_b32_e32 v2, 7, v0
	s_nop 0
	v_cndmask_b32_e32 v102, v225, v102, vcc
	v_cmp_le_i32_e32 vcc, v2, v153
	v_or_b32_e32 v2, 16, v0
	s_nop 0
	v_cndmask_b32_e32 v103, v225, v103, vcc
	v_cmp_le_i32_e32 vcc, v2, v153
	v_or_b32_e32 v2, 17, v0
	s_nop 0
	v_cndmask_b32_e32 v104, v225, v104, vcc
	v_cmp_le_i32_e32 vcc, v2, v153
	v_or_b32_e32 v2, 18, v0
	s_nop 0
	v_cndmask_b32_e32 v105, v225, v105, vcc
	v_cmp_le_i32_e32 vcc, v2, v153
	v_or_b32_e32 v2, 19, v0
	s_nop 0
	v_cndmask_b32_e32 v106, v225, v106, vcc
	v_cmp_le_i32_e32 vcc, v2, v153
	v_or_b32_e32 v2, 20, v0
	s_nop 0
	v_cndmask_b32_e32 v107, v225, v107, vcc
	v_cmp_le_i32_e32 vcc, v2, v153
	v_or_b32_e32 v2, 21, v0
	s_nop 0
	v_cndmask_b32_e32 v108, v225, v108, vcc
	v_cmp_le_i32_e32 vcc, v2, v153
	v_or_b32_e32 v2, 22, v0
	s_nop 0
	v_cndmask_b32_e32 v109, v225, v109, vcc
	v_cmp_le_i32_e32 vcc, v2, v153
	v_or_b32_e32 v2, 23, v0
	s_nop 0
	v_cndmask_b32_e32 v110, v225, v110, vcc
	v_cmp_le_i32_e32 vcc, v2, v153
	v_or_b32_e32 v2, 32, v0
	s_nop 0
	v_cndmask_b32_e32 v111, v225, v111, vcc
	v_cmp_le_i32_e32 vcc, v2, v153
	v_or_b32_e32 v2, 33, v0
	s_nop 0
	v_cndmask_b32_e32 v80, v225, v80, vcc
	v_cmp_le_i32_e32 vcc, v2, v153
	v_or_b32_e32 v2, 34, v0
	s_nop 0
	v_cndmask_b32_e32 v81, v225, v81, vcc
	v_cmp_le_i32_e32 vcc, v2, v153
	v_or_b32_e32 v2, 35, v0
	s_nop 0
	v_cndmask_b32_e32 v82, v225, v82, vcc
	v_cmp_le_i32_e32 vcc, v2, v153
	v_or_b32_e32 v2, 36, v0
	s_nop 0
	v_cndmask_b32_e32 v83, v225, v83, vcc
	v_cmp_le_i32_e32 vcc, v2, v153
	v_or_b32_e32 v2, 37, v0
	s_nop 0
	v_cndmask_b32_e32 v84, v225, v84, vcc
	v_cmp_le_i32_e32 vcc, v2, v153
	v_or_b32_e32 v2, 38, v0
	s_nop 0
	v_cndmask_b32_e32 v85, v225, v85, vcc
	v_cmp_le_i32_e32 vcc, v2, v153
	v_or_b32_e32 v2, 39, v0
	s_nop 0
	v_cndmask_b32_e32 v86, v225, v86, vcc
	v_cmp_le_i32_e32 vcc, v2, v153
	v_or_b32_e32 v2, 48, v0
	s_nop 0
	v_cndmask_b32_e32 v87, v225, v87, vcc
	v_cmp_le_i32_e32 vcc, v2, v153
	v_or_b32_e32 v2, 49, v0
	s_nop 0
	v_cndmask_b32_e32 v88, v225, v88, vcc
	v_cmp_le_i32_e32 vcc, v2, v153
	v_or_b32_e32 v2, 50, v0
	s_nop 0
	v_cndmask_b32_e32 v89, v225, v89, vcc
	v_cmp_le_i32_e32 vcc, v2, v153
	v_or_b32_e32 v2, 51, v0
	s_nop 0
	v_cndmask_b32_e32 v90, v225, v90, vcc
	v_cmp_le_i32_e32 vcc, v2, v153
	v_or_b32_e32 v2, 52, v0
	s_nop 0
	v_cndmask_b32_e32 v91, v225, v91, vcc
	v_cmp_le_i32_e32 vcc, v2, v153
	v_or_b32_e32 v2, 53, v0
	s_nop 0
	v_cndmask_b32_e32 v92, v225, v92, vcc
	v_cmp_le_i32_e32 vcc, v2, v153
	v_or_b32_e32 v2, 54, v0
	v_or_b32_e32 v0, 55, v0
	v_cndmask_b32_e32 v93, v225, v93, vcc
	v_cmp_le_i32_e32 vcc, v2, v153
	s_nop 1
	v_cndmask_b32_e32 v94, v225, v94, vcc
	v_cmp_le_i32_e32 vcc, v0, v153
	s_nop 1
	v_cndmask_b32_e32 v95, v225, v95, vcc
